# GEMM MFMA blocks: snake order (every other 4-pair group reversed so the first-source pair repeats across the group boundary), chained k0/k1 pairs kept
# speedup vs baseline: 1.0059x; 1.0046x over previous
.LBB0_260:
	v_add_u32_e32 v168, 0x10000, v232
	v_add_u32_e32 v180, 0x14000, v232
	v_lshl_add_u64 v[224:225], v[222:223], 0, s[62:63]
	s_add_i32 m0, s35, 0xc000
	s_waitcnt lgkmcnt(0)
	ds_read_b128 v[148:151], v207
	ds_read_b128 v[164:167], v207 offset:1024
	ds_read_b128 v[144:147], v207 offset:2048
	ds_read_b128 v[160:163], v207 offset:3072
	ds_read_b128 v[140:143], v207 offset:4096
	ds_read_b128 v[156:159], v207 offset:5120
	ds_read_b128 v[136:139], v207 offset:6144
	ds_read_b128 v[152:155], v207 offset:7168
	ds_read_b128 v[184:187], v168
	ds_read_b128 v[188:191], v168 offset:1024
	ds_read_b128 v[192:195], v168 offset:2048
	ds_read_b128 v[196:199], v168 offset:3072
	ds_read_b128 v[168:171], v180
	ds_read_b128 v[172:175], v180 offset:1024
	ds_read_b128 v[176:179], v180 offset:2048
	ds_read_b128 v[180:183], v180 offset:3072
	global_load_lds_dwordx4 v[224:225], off
	v_lshl_add_u64 v[224:225], v[220:221], 0, s[62:63]
	s_add_i32 m0, s35, 0xe000
	s_nop 0
	global_load_lds_dwordx4 v[224:225], off
	s_waitcnt vmcnt(8)
	s_waitcnt lgkmcnt(0)
	s_barrier
	s_waitcnt lgkmcnt(0)
	v_mfma_f32_16x16x32_bf16 v[132:135], v[184:187], v[148:151], v[132:135]
	v_mfma_f32_16x16x32_bf16 v[132:135], v[188:191], v[164:167], v[132:135]
	v_mfma_f32_16x16x32_bf16 v[128:131], v[192:195], v[148:151], v[128:131]
	v_mfma_f32_16x16x32_bf16 v[128:131], v[196:199], v[164:167], v[128:131]
	v_mfma_f32_16x16x32_bf16 v[124:127], v[168:171], v[148:151], v[124:127]
	v_mfma_f32_16x16x32_bf16 v[124:127], v[172:175], v[164:167], v[124:127]
	v_mfma_f32_16x16x32_bf16 v[120:123], v[176:179], v[148:151], v[120:123]
	v_mfma_f32_16x16x32_bf16 v[120:123], v[180:183], v[164:167], v[120:123]
	v_mfma_f32_16x16x32_bf16 v[104:107], v[176:179], v[144:147], v[104:107]
	v_mfma_f32_16x16x32_bf16 v[104:107], v[180:183], v[160:163], v[104:107]
	v_mfma_f32_16x16x32_bf16 v[108:111], v[168:171], v[144:147], v[108:111]
	v_mfma_f32_16x16x32_bf16 v[108:111], v[172:175], v[160:163], v[108:111]
	v_mfma_f32_16x16x32_bf16 v[112:115], v[192:195], v[144:147], v[112:115]
	v_mfma_f32_16x16x32_bf16 v[112:115], v[196:199], v[160:163], v[112:115]
	v_mfma_f32_16x16x32_bf16 v[116:119], v[184:187], v[144:147], v[116:119]
	v_mfma_f32_16x16x32_bf16 v[116:119], v[188:191], v[160:163], v[116:119]
	v_mfma_f32_16x16x32_bf16 v[100:103], v[184:187], v[140:143], v[100:103]
	v_mfma_f32_16x16x32_bf16 v[100:103], v[188:191], v[156:159], v[100:103]
	v_mfma_f32_16x16x32_bf16 v[96:99], v[192:195], v[140:143], v[96:99]
	v_mfma_f32_16x16x32_bf16 v[96:99], v[196:199], v[156:159], v[96:99]
	v_mfma_f32_16x16x32_bf16 v[92:95], v[168:171], v[140:143], v[92:95]
	v_mfma_f32_16x16x32_bf16 v[92:95], v[172:175], v[156:159], v[92:95]
	v_mfma_f32_16x16x32_bf16 v[88:91], v[176:179], v[140:143], v[88:91]
	v_mfma_f32_16x16x32_bf16 v[88:91], v[180:183], v[156:159], v[88:91]
	v_mfma_f32_16x16x32_bf16 v[72:75], v[176:179], v[136:139], v[72:75]
	v_mfma_f32_16x16x32_bf16 v[72:75], v[180:183], v[152:155], v[72:75]
	v_mfma_f32_16x16x32_bf16 v[76:79], v[168:171], v[136:139], v[76:79]
	v_mfma_f32_16x16x32_bf16 v[76:79], v[172:175], v[152:155], v[76:79]
	v_mfma_f32_16x16x32_bf16 v[80:83], v[192:195], v[136:139], v[80:83]
	v_mfma_f32_16x16x32_bf16 v[80:83], v[196:199], v[152:155], v[80:83]
	v_mfma_f32_16x16x32_bf16 v[84:87], v[184:187], v[136:139], v[84:87]
	v_mfma_f32_16x16x32_bf16 v[84:87], v[188:191], v[152:155], v[84:87]
	s_barrier
	v_cndmask_b32_e64 v204, 0, 1, s[60:61]
	v_cmp_ne_u32_e64 s[50:51], 1, v204
	s_andn2_b64 vcc, exec, s[60:61]
	s_cbranch_vccnz .LBB0_262
	ds_read_b128 v[148:151], v207 offset:16384
	ds_read_b128 v[164:167], v207 offset:17408
	ds_read_b128 v[144:147], v207 offset:18432
	ds_read_b128 v[160:163], v207 offset:19456
	ds_read_b128 v[140:143], v207 offset:20480
	ds_read_b128 v[156:159], v207 offset:21504
	ds_read_b128 v[136:139], v207 offset:22528
	ds_read_b128 v[152:155], v207 offset:23552
.LBB0_262:
	s_add_u32 s12, s58, s62
	s_addc_u32 s13, s59, s63
	s_add_u32 s14, s12, 0x100
	s_addc_u32 s15, s13, 0
	s_add_u32 s75, s26, s62
	s_addc_u32 s76, s27, s63
	s_cmpk_eq_i32 s62, 0xf00
	s_cselect_b64 s[52:53], -1, 0
	s_and_b64 s[12:13], s[52:53], exec
	s_cselect_b32 s13, s21, s76
	s_cselect_b32 s12, s73, s75
	s_mov_b32 m0, s38
	s_cselect_b32 s15, s25, s15
	s_cselect_b32 s14, s33, s14
	v_lshl_add_u64 v[224:225], s[12:13], 0, v[208:209]
	s_add_u32 s76, s12, 0x80000
	global_load_lds_dwordx4 v[224:225], off
	v_lshl_add_u64 v[226:227], s[12:13], 0, v[212:213]
	s_mov_b32 m0, s39
	s_addc_u32 s77, s13, 0
	global_load_lds_dwordx4 v[226:227], off
	v_lshl_add_u64 v[228:229], s[76:77], 0, v[208:209]
	s_mov_b32 m0, s40
	v_lshl_add_u64 v[230:231], s[14:15], 0, v[210:211]
	global_load_lds_dwordx4 v[228:229], off
	v_lshl_add_u64 v[228:229], s[76:77], 0, v[212:213]
	s_mov_b32 m0, s41
	s_and_b64 vcc, exec, s[50:51]
	global_load_lds_dwordx4 v[228:229], off
	v_lshl_add_u64 v[228:229], s[14:15], 0, v[4:5]
	s_mov_b32 m0, s35
	s_nop 0
	global_load_lds_dwordx4 v[228:229], off
	s_mov_b32 m0, s43
	s_nop 0
	global_load_lds_dwordx4 v[230:231], off
	s_waitcnt vmcnt(8)
	s_waitcnt lgkmcnt(0)
	s_barrier
	s_cbranch_vccnz .LBB0_264
	s_waitcnt lgkmcnt(0)
	v_mfma_f32_16x16x32_bf16 v[68:71], v[184:187], v[148:151], v[68:71]
	v_mfma_f32_16x16x32_bf16 v[68:71], v[188:191], v[164:167], v[68:71]
	v_mfma_f32_16x16x32_bf16 v[64:67], v[192:195], v[148:151], v[64:67]
	v_mfma_f32_16x16x32_bf16 v[64:67], v[196:199], v[164:167], v[64:67]
	v_mfma_f32_16x16x32_bf16 v[60:63], v[168:171], v[148:151], v[60:63]
	v_mfma_f32_16x16x32_bf16 v[60:63], v[172:175], v[164:167], v[60:63]
	v_mfma_f32_16x16x32_bf16 v[56:59], v[176:179], v[148:151], v[56:59]
	v_mfma_f32_16x16x32_bf16 v[56:59], v[180:183], v[164:167], v[56:59]
	v_mfma_f32_16x16x32_bf16 v[40:43], v[176:179], v[144:147], v[40:43]
	v_mfma_f32_16x16x32_bf16 v[40:43], v[180:183], v[160:163], v[40:43]
	v_mfma_f32_16x16x32_bf16 v[44:47], v[168:171], v[144:147], v[44:47]
	v_mfma_f32_16x16x32_bf16 v[44:47], v[172:175], v[160:163], v[44:47]
	v_mfma_f32_16x16x32_bf16 v[48:51], v[192:195], v[144:147], v[48:51]
	v_mfma_f32_16x16x32_bf16 v[48:51], v[196:199], v[160:163], v[48:51]
	v_mfma_f32_16x16x32_bf16 v[52:55], v[184:187], v[144:147], v[52:55]
	v_mfma_f32_16x16x32_bf16 v[52:55], v[188:191], v[160:163], v[52:55]
	v_mfma_f32_16x16x32_bf16 v[36:39], v[184:187], v[140:143], v[36:39]
	v_mfma_f32_16x16x32_bf16 v[36:39], v[188:191], v[156:159], v[36:39]
	v_mfma_f32_16x16x32_bf16 v[32:35], v[192:195], v[140:143], v[32:35]
	v_mfma_f32_16x16x32_bf16 v[32:35], v[196:199], v[156:159], v[32:35]
	v_mfma_f32_16x16x32_bf16 v[28:31], v[168:171], v[140:143], v[28:31]
	v_mfma_f32_16x16x32_bf16 v[28:31], v[172:175], v[156:159], v[28:31]
	v_mfma_f32_16x16x32_bf16 v[24:27], v[176:179], v[140:143], v[24:27]
	v_mfma_f32_16x16x32_bf16 v[24:27], v[180:183], v[156:159], v[24:27]
	v_mfma_f32_16x16x32_bf16 v[8:11], v[176:179], v[136:139], v[8:11]
	v_mfma_f32_16x16x32_bf16 v[8:11], v[180:183], v[152:155], v[8:11]
	v_mfma_f32_16x16x32_bf16 v[12:15], v[168:171], v[136:139], v[12:15]
	v_mfma_f32_16x16x32_bf16 v[12:15], v[172:175], v[152:155], v[12:15]
	v_mfma_f32_16x16x32_bf16 v[16:19], v[192:195], v[136:139], v[16:19]
	v_mfma_f32_16x16x32_bf16 v[16:19], v[196:199], v[152:155], v[16:19]
	v_mfma_f32_16x16x32_bf16 v[20:23], v[184:187], v[136:139], v[20:23]
	v_mfma_f32_16x16x32_bf16 v[20:23], v[188:191], v[152:155], v[20:23]
.LBB0_264:
	s_barrier
	v_cndmask_b32_e64 v241, v219, 0, s[52:53]
	v_cndmask_b32_e64 v240, v218, v2, s[52:53]
	v_lshl_add_u64 v[240:241], s[14:15], 0, v[240:241]
	s_mov_b32 m0, s45
	v_add_u32_e32 v168, 0x18000, v232
	v_add_u32_e32 v180, 0x1c000, v232
	v_lshl_add_u64 v[242:243], v[240:241], 0, v[4:5]
	s_waitcnt lgkmcnt(0)
	ds_read_b128 v[148:151], v207 offset:32768
	ds_read_b128 v[164:167], v207 offset:33792
	ds_read_b128 v[144:147], v207 offset:34816
	ds_read_b128 v[160:163], v207 offset:35840
	ds_read_b128 v[140:143], v207 offset:36864
	ds_read_b128 v[156:159], v207 offset:37888
	ds_read_b128 v[136:139], v207 offset:38912
	ds_read_b128 v[152:155], v207 offset:39936
	ds_read_b128 v[184:187], v168
	ds_read_b128 v[188:191], v168 offset:1024
	ds_read_b128 v[192:195], v168 offset:2048
	ds_read_b128 v[196:199], v168 offset:3072
	ds_read_b128 v[168:171], v180
	ds_read_b128 v[172:175], v180 offset:1024
	ds_read_b128 v[176:179], v180 offset:2048
	ds_read_b128 v[180:183], v180 offset:3072
	global_load_lds_dwordx4 v[242:243], off
	v_lshl_add_u64 v[240:241], v[240:241], 0, v[210:211]
	s_mov_b32 m0, s47
	s_nop 0
	global_load_lds_dwordx4 v[240:241], off
	s_waitcnt vmcnt(8)
	s_waitcnt lgkmcnt(0)
	s_barrier
	s_waitcnt lgkmcnt(0)
	v_mfma_f32_16x16x32_bf16 v[132:135], v[184:187], v[148:151], v[132:135]
	v_mfma_f32_16x16x32_bf16 v[132:135], v[188:191], v[164:167], v[132:135]
	v_mfma_f32_16x16x32_bf16 v[128:131], v[192:195], v[148:151], v[128:131]
	v_mfma_f32_16x16x32_bf16 v[128:131], v[196:199], v[164:167], v[128:131]
	v_mfma_f32_16x16x32_bf16 v[124:127], v[168:171], v[148:151], v[124:127]
	v_mfma_f32_16x16x32_bf16 v[124:127], v[172:175], v[164:167], v[124:127]
	v_mfma_f32_16x16x32_bf16 v[120:123], v[176:179], v[148:151], v[120:123]
	v_mfma_f32_16x16x32_bf16 v[120:123], v[180:183], v[164:167], v[120:123]
	v_mfma_f32_16x16x32_bf16 v[104:107], v[176:179], v[144:147], v[104:107]
	v_mfma_f32_16x16x32_bf16 v[104:107], v[180:183], v[160:163], v[104:107]
	v_mfma_f32_16x16x32_bf16 v[108:111], v[168:171], v[144:147], v[108:111]
	v_mfma_f32_16x16x32_bf16 v[108:111], v[172:175], v[160:163], v[108:111]
	v_mfma_f32_16x16x32_bf16 v[112:115], v[192:195], v[144:147], v[112:115]
	v_mfma_f32_16x16x32_bf16 v[112:115], v[196:199], v[160:163], v[112:115]
	v_mfma_f32_16x16x32_bf16 v[116:119], v[184:187], v[144:147], v[116:119]
	v_mfma_f32_16x16x32_bf16 v[116:119], v[188:191], v[160:163], v[116:119]
	v_mfma_f32_16x16x32_bf16 v[100:103], v[184:187], v[140:143], v[100:103]
	v_mfma_f32_16x16x32_bf16 v[100:103], v[188:191], v[156:159], v[100:103]
	v_mfma_f32_16x16x32_bf16 v[96:99], v[192:195], v[140:143], v[96:99]
	v_mfma_f32_16x16x32_bf16 v[96:99], v[196:199], v[156:159], v[96:99]
	v_mfma_f32_16x16x32_bf16 v[92:95], v[168:171], v[140:143], v[92:95]
	v_mfma_f32_16x16x32_bf16 v[92:95], v[172:175], v[156:159], v[92:95]
	v_mfma_f32_16x16x32_bf16 v[88:91], v[176:179], v[140:143], v[88:91]
	v_mfma_f32_16x16x32_bf16 v[88:91], v[180:183], v[156:159], v[88:91]
	v_mfma_f32_16x16x32_bf16 v[72:75], v[176:179], v[136:139], v[72:75]
	v_mfma_f32_16x16x32_bf16 v[72:75], v[180:183], v[152:155], v[72:75]
	v_mfma_f32_16x16x32_bf16 v[76:79], v[168:171], v[136:139], v[76:79]
	v_mfma_f32_16x16x32_bf16 v[76:79], v[172:175], v[152:155], v[76:79]
	v_mfma_f32_16x16x32_bf16 v[80:83], v[192:195], v[136:139], v[80:83]
	v_mfma_f32_16x16x32_bf16 v[80:83], v[196:199], v[152:155], v[80:83]
	v_mfma_f32_16x16x32_bf16 v[84:87], v[184:187], v[136:139], v[84:87]
	v_mfma_f32_16x16x32_bf16 v[84:87], v[188:191], v[152:155], v[84:87]
	s_barrier
	s_and_b64 vcc, exec, s[50:51]
	s_cbranch_vccnz .LBB0_266
	ds_read_b128 v[148:151], v207 offset:49152
	ds_read_b128 v[164:167], v207 offset:50176
	ds_read_b128 v[144:147], v207 offset:51200
	ds_read_b128 v[160:163], v207 offset:52224
	ds_read_b128 v[140:143], v207 offset:53248
	ds_read_b128 v[156:159], v207 offset:54272
	ds_read_b128 v[136:139], v207 offset:55296
	ds_read_b128 v[152:155], v207 offset:56320
.LBB0_266:
	s_mov_b32 m0, s64
	v_lshl_add_u64 v[224:225], v[224:225], 0, s[0:1]
	s_add_u32 s12, s12, 0x80080
	global_load_lds_dwordx4 v[224:225], off
	v_lshl_add_u64 v[224:225], v[226:227], 0, s[0:1]
	s_mov_b32 m0, s65
	s_addc_u32 s13, s13, 0
	global_load_lds_dwordx4 v[224:225], off
	v_lshl_add_u64 v[224:225], s[12:13], 0, v[208:209]
	s_mov_b32 m0, s68
	s_and_b64 vcc, exec, s[50:51]
	global_load_lds_dwordx4 v[224:225], off
	v_lshl_add_u64 v[224:225], s[12:13], 0, v[212:213]
	s_mov_b32 m0, s69
	s_nop 0
	global_load_lds_dwordx4 v[224:225], off
	v_lshl_add_u64 v[224:225], v[228:229], 0, s[0:1]
	s_mov_b32 m0, s66
	s_nop 0
	global_load_lds_dwordx4 v[224:225], off
	v_lshl_add_u64 v[224:225], v[230:231], 0, s[0:1]
	s_mov_b32 m0, s67
	s_nop 0
	global_load_lds_dwordx4 v[224:225], off
	s_waitcnt vmcnt(8)
	s_waitcnt lgkmcnt(0)
	s_barrier
	s_cbranch_vccnz .LBB0_259
	s_waitcnt lgkmcnt(0)
	v_mfma_f32_16x16x32_bf16 v[68:71], v[184:187], v[148:151], v[68:71]
	v_mfma_f32_16x16x32_bf16 v[68:71], v[188:191], v[164:167], v[68:71]
	v_mfma_f32_16x16x32_bf16 v[64:67], v[192:195], v[148:151], v[64:67]
	v_mfma_f32_16x16x32_bf16 v[64:67], v[196:199], v[164:167], v[64:67]
	v_mfma_f32_16x16x32_bf16 v[60:63], v[168:171], v[148:151], v[60:63]
	v_mfma_f32_16x16x32_bf16 v[60:63], v[172:175], v[164:167], v[60:63]
	v_mfma_f32_16x16x32_bf16 v[56:59], v[176:179], v[148:151], v[56:59]
	v_mfma_f32_16x16x32_bf16 v[56:59], v[180:183], v[164:167], v[56:59]
	v_mfma_f32_16x16x32_bf16 v[40:43], v[176:179], v[144:147], v[40:43]
	v_mfma_f32_16x16x32_bf16 v[40:43], v[180:183], v[160:163], v[40:43]
	v_mfma_f32_16x16x32_bf16 v[44:47], v[168:171], v[144:147], v[44:47]
	v_mfma_f32_16x16x32_bf16 v[44:47], v[172:175], v[160:163], v[44:47]
	v_mfma_f32_16x16x32_bf16 v[48:51], v[192:195], v[144:147], v[48:51]
	v_mfma_f32_16x16x32_bf16 v[48:51], v[196:199], v[160:163], v[48:51]
	v_mfma_f32_16x16x32_bf16 v[52:55], v[184:187], v[144:147], v[52:55]
	v_mfma_f32_16x16x32_bf16 v[52:55], v[188:191], v[160:163], v[52:55]
	v_mfma_f32_16x16x32_bf16 v[36:39], v[184:187], v[140:143], v[36:39]
	v_mfma_f32_16x16x32_bf16 v[36:39], v[188:191], v[156:159], v[36:39]
	v_mfma_f32_16x16x32_bf16 v[32:35], v[192:195], v[140:143], v[32:35]
	v_mfma_f32_16x16x32_bf16 v[32:35], v[196:199], v[156:159], v[32:35]
	v_mfma_f32_16x16x32_bf16 v[28:31], v[168:171], v[140:143], v[28:31]
	v_mfma_f32_16x16x32_bf16 v[28:31], v[172:175], v[156:159], v[28:31]
	v_mfma_f32_16x16x32_bf16 v[24:27], v[176:179], v[140:143], v[24:27]
	v_mfma_f32_16x16x32_bf16 v[24:27], v[180:183], v[156:159], v[24:27]
	v_mfma_f32_16x16x32_bf16 v[8:11], v[176:179], v[136:139], v[8:11]
	v_mfma_f32_16x16x32_bf16 v[8:11], v[180:183], v[152:155], v[8:11]
	v_mfma_f32_16x16x32_bf16 v[12:15], v[168:171], v[136:139], v[12:15]
	v_mfma_f32_16x16x32_bf16 v[12:15], v[172:175], v[152:155], v[12:15]
	v_mfma_f32_16x16x32_bf16 v[16:19], v[192:195], v[136:139], v[16:19]
	v_mfma_f32_16x16x32_bf16 v[16:19], v[196:199], v[152:155], v[16:19]
	v_mfma_f32_16x16x32_bf16 v[20:23], v[184:187], v[136:139], v[20:23]
	v_mfma_f32_16x16x32_bf16 v[20:23], v[188:191], v[152:155], v[20:23]
	s_branch .LBB0_259

.LBB0_369:
	v_add_u32_e32 v168, 0x10000, v232
	v_add_u32_e32 v180, 0x14000, v232
	v_lshl_add_u64 v[224:225], v[222:223], 0, s[60:61]
	s_add_i32 m0, s9, 0xc000
	s_waitcnt lgkmcnt(0)
	ds_read_b128 v[148:151], v207
	ds_read_b128 v[164:167], v207 offset:1024
	ds_read_b128 v[144:147], v207 offset:2048
	ds_read_b128 v[160:163], v207 offset:3072
	ds_read_b128 v[140:143], v207 offset:4096
	ds_read_b128 v[156:159], v207 offset:5120
	ds_read_b128 v[136:139], v207 offset:6144
	ds_read_b128 v[152:155], v207 offset:7168
	ds_read_b128 v[184:187], v168
	ds_read_b128 v[188:191], v168 offset:1024
	ds_read_b128 v[192:195], v168 offset:2048
	ds_read_b128 v[196:199], v168 offset:3072
	ds_read_b128 v[168:171], v180
	ds_read_b128 v[172:175], v180 offset:1024
	ds_read_b128 v[176:179], v180 offset:2048
	ds_read_b128 v[180:183], v180 offset:3072
	global_load_lds_dwordx4 v[224:225], off
	v_lshl_add_u64 v[224:225], v[220:221], 0, s[60:61]
	s_add_i32 m0, s9, 0xe000
	s_nop 0
	global_load_lds_dwordx4 v[224:225], off
	s_waitcnt vmcnt(8)
	s_waitcnt lgkmcnt(0)
	s_barrier
	s_waitcnt lgkmcnt(0)
	v_mfma_f32_16x16x32_bf16 v[132:135], v[184:187], v[148:151], v[132:135]
	v_mfma_f32_16x16x32_bf16 v[132:135], v[188:191], v[164:167], v[132:135]
	v_mfma_f32_16x16x32_bf16 v[128:131], v[192:195], v[148:151], v[128:131]
	v_mfma_f32_16x16x32_bf16 v[128:131], v[196:199], v[164:167], v[128:131]
	v_mfma_f32_16x16x32_bf16 v[116:119], v[168:171], v[148:151], v[116:119]
	v_mfma_f32_16x16x32_bf16 v[116:119], v[172:175], v[164:167], v[116:119]
	v_mfma_f32_16x16x32_bf16 v[112:115], v[176:179], v[148:151], v[112:115]
	v_mfma_f32_16x16x32_bf16 v[112:115], v[180:183], v[164:167], v[112:115]
	v_mfma_f32_16x16x32_bf16 v[96:99], v[176:179], v[144:147], v[96:99]
	v_mfma_f32_16x16x32_bf16 v[96:99], v[180:183], v[160:163], v[96:99]
	v_mfma_f32_16x16x32_bf16 v[100:103], v[168:171], v[144:147], v[100:103]
	v_mfma_f32_16x16x32_bf16 v[100:103], v[172:175], v[160:163], v[100:103]
	v_mfma_f32_16x16x32_bf16 v[120:123], v[192:195], v[144:147], v[120:123]
	v_mfma_f32_16x16x32_bf16 v[120:123], v[196:199], v[160:163], v[120:123]
	v_mfma_f32_16x16x32_bf16 v[124:127], v[184:187], v[144:147], v[124:127]
	v_mfma_f32_16x16x32_bf16 v[124:127], v[188:191], v[160:163], v[124:127]
	v_mfma_f32_16x16x32_bf16 v[108:111], v[184:187], v[140:143], v[108:111]
	v_mfma_f32_16x16x32_bf16 v[108:111], v[188:191], v[156:159], v[108:111]
	v_mfma_f32_16x16x32_bf16 v[104:107], v[192:195], v[140:143], v[104:107]
	v_mfma_f32_16x16x32_bf16 v[104:107], v[196:199], v[156:159], v[104:107]
	v_mfma_f32_16x16x32_bf16 v[84:87], v[168:171], v[140:143], v[84:87]
	v_mfma_f32_16x16x32_bf16 v[84:87], v[172:175], v[156:159], v[84:87]
	v_mfma_f32_16x16x32_bf16 v[80:83], v[176:179], v[140:143], v[80:83]
	v_mfma_f32_16x16x32_bf16 v[80:83], v[180:183], v[156:159], v[80:83]
	v_mfma_f32_16x16x32_bf16 v[72:75], v[176:179], v[136:139], v[72:75]
	v_mfma_f32_16x16x32_bf16 v[72:75], v[180:183], v[152:155], v[72:75]
	v_mfma_f32_16x16x32_bf16 v[76:79], v[168:171], v[136:139], v[76:79]
	v_mfma_f32_16x16x32_bf16 v[76:79], v[172:175], v[152:155], v[76:79]
	v_mfma_f32_16x16x32_bf16 v[88:91], v[192:195], v[136:139], v[88:91]
	v_mfma_f32_16x16x32_bf16 v[88:91], v[196:199], v[152:155], v[88:91]
	v_mfma_f32_16x16x32_bf16 v[92:95], v[184:187], v[136:139], v[92:95]
	v_mfma_f32_16x16x32_bf16 v[92:95], v[188:191], v[152:155], v[92:95]
	s_barrier
	v_cndmask_b32_e64 v204, 0, 1, s[58:59]
	v_cmp_ne_u32_e64 s[50:51], 1, v204
	s_andn2_b64 vcc, exec, s[58:59]
	s_cbranch_vccnz .LBB0_371
	ds_read_b128 v[148:151], v207 offset:16384
	ds_read_b128 v[164:167], v207 offset:17408
	ds_read_b128 v[144:147], v207 offset:18432
	ds_read_b128 v[160:163], v207 offset:19456
	ds_read_b128 v[140:143], v207 offset:20480
	ds_read_b128 v[156:159], v207 offset:21504
	ds_read_b128 v[136:139], v207 offset:22528
	ds_read_b128 v[152:155], v207 offset:23552
.LBB0_371:
	s_add_u32 s12, s24, s60
	s_addc_u32 s13, s25, s61
	s_add_u32 s14, s12, 0x100
	s_addc_u32 s15, s13, 0
	s_add_u32 s73, s26, s60
	s_addc_u32 s74, s27, s61
	s_cmpk_eq_i32 s60, 0xf00
	s_cselect_b64 s[52:53], -1, 0
	s_and_b64 s[12:13], s[52:53], exec
	s_cselect_b32 s13, s37, s74
	s_cselect_b32 s12, s43, s73
	s_mov_b32 m0, s38
	s_cselect_b32 s15, s7, s15
	s_cselect_b32 s14, s33, s14
	v_lshl_add_u64 v[224:225], s[12:13], 0, v[208:209]
	s_add_u32 s74, s12, 0x80000
	global_load_lds_dwordx4 v[224:225], off
	v_lshl_add_u64 v[226:227], s[12:13], 0, v[212:213]
	s_mov_b32 m0, s39
	s_addc_u32 s75, s13, 0
	global_load_lds_dwordx4 v[226:227], off
	v_lshl_add_u64 v[228:229], s[74:75], 0, v[208:209]
	s_mov_b32 m0, s40
	v_lshl_add_u64 v[230:231], s[14:15], 0, v[210:211]
	global_load_lds_dwordx4 v[228:229], off
	v_lshl_add_u64 v[228:229], s[74:75], 0, v[212:213]
	s_mov_b32 m0, s41
	s_and_b64 vcc, exec, s[50:51]
	global_load_lds_dwordx4 v[228:229], off
	v_lshl_add_u64 v[228:229], s[14:15], 0, v[4:5]
	s_mov_b32 m0, s9
	s_nop 0
	global_load_lds_dwordx4 v[228:229], off
	s_mov_b32 m0, s47
	s_nop 0
	global_load_lds_dwordx4 v[230:231], off
	s_waitcnt vmcnt(8)
	s_waitcnt lgkmcnt(0)
	s_barrier
	s_cbranch_vccnz .LBB0_373
	s_waitcnt lgkmcnt(0)
	v_mfma_f32_16x16x32_bf16 v[68:71], v[184:187], v[148:151], v[68:71]
	v_mfma_f32_16x16x32_bf16 v[68:71], v[188:191], v[164:167], v[68:71]
	v_mfma_f32_16x16x32_bf16 v[64:67], v[192:195], v[148:151], v[64:67]
	v_mfma_f32_16x16x32_bf16 v[64:67], v[196:199], v[164:167], v[64:67]
	v_mfma_f32_16x16x32_bf16 v[60:63], v[168:171], v[148:151], v[60:63]
	v_mfma_f32_16x16x32_bf16 v[60:63], v[172:175], v[164:167], v[60:63]
	v_mfma_f32_16x16x32_bf16 v[56:59], v[176:179], v[148:151], v[56:59]
	v_mfma_f32_16x16x32_bf16 v[56:59], v[180:183], v[164:167], v[56:59]
	v_mfma_f32_16x16x32_bf16 v[40:43], v[176:179], v[144:147], v[40:43]
	v_mfma_f32_16x16x32_bf16 v[40:43], v[180:183], v[160:163], v[40:43]
	v_mfma_f32_16x16x32_bf16 v[44:47], v[168:171], v[144:147], v[44:47]
	v_mfma_f32_16x16x32_bf16 v[44:47], v[172:175], v[160:163], v[44:47]
	v_mfma_f32_16x16x32_bf16 v[48:51], v[192:195], v[144:147], v[48:51]
	v_mfma_f32_16x16x32_bf16 v[48:51], v[196:199], v[160:163], v[48:51]
	v_mfma_f32_16x16x32_bf16 v[52:55], v[184:187], v[144:147], v[52:55]
	v_mfma_f32_16x16x32_bf16 v[52:55], v[188:191], v[160:163], v[52:55]
	v_mfma_f32_16x16x32_bf16 v[36:39], v[184:187], v[140:143], v[36:39]
	v_mfma_f32_16x16x32_bf16 v[36:39], v[188:191], v[156:159], v[36:39]
	v_mfma_f32_16x16x32_bf16 v[32:35], v[192:195], v[140:143], v[32:35]
	v_mfma_f32_16x16x32_bf16 v[32:35], v[196:199], v[156:159], v[32:35]
	v_mfma_f32_16x16x32_bf16 v[28:31], v[168:171], v[140:143], v[28:31]
	v_mfma_f32_16x16x32_bf16 v[28:31], v[172:175], v[156:159], v[28:31]
	v_mfma_f32_16x16x32_bf16 v[24:27], v[176:179], v[140:143], v[24:27]
	v_mfma_f32_16x16x32_bf16 v[24:27], v[180:183], v[156:159], v[24:27]
	v_mfma_f32_16x16x32_bf16 v[8:11], v[176:179], v[136:139], v[8:11]
	v_mfma_f32_16x16x32_bf16 v[8:11], v[180:183], v[152:155], v[8:11]
	v_mfma_f32_16x16x32_bf16 v[12:15], v[168:171], v[136:139], v[12:15]
	v_mfma_f32_16x16x32_bf16 v[12:15], v[172:175], v[152:155], v[12:15]
	v_mfma_f32_16x16x32_bf16 v[16:19], v[192:195], v[136:139], v[16:19]
	v_mfma_f32_16x16x32_bf16 v[16:19], v[196:199], v[152:155], v[16:19]
	v_mfma_f32_16x16x32_bf16 v[20:23], v[184:187], v[136:139], v[20:23]
	v_mfma_f32_16x16x32_bf16 v[20:23], v[188:191], v[152:155], v[20:23]
.LBB0_373:
	s_barrier
	v_cndmask_b32_e64 v241, v219, 0, s[52:53]
	v_cndmask_b32_e64 v240, v218, v2, s[52:53]
	v_lshl_add_u64 v[240:241], s[14:15], 0, v[240:241]
	s_mov_b32 m0, s62
	v_add_u32_e32 v168, 0x18000, v232
	v_add_u32_e32 v180, 0x1c000, v232
	v_lshl_add_u64 v[242:243], v[240:241], 0, v[4:5]
	s_waitcnt lgkmcnt(0)
	ds_read_b128 v[148:151], v207 offset:32768
	ds_read_b128 v[164:167], v207 offset:33792
	ds_read_b128 v[144:147], v207 offset:34816
	ds_read_b128 v[160:163], v207 offset:35840
	ds_read_b128 v[140:143], v207 offset:36864
	ds_read_b128 v[156:159], v207 offset:37888
	ds_read_b128 v[136:139], v207 offset:38912
	ds_read_b128 v[152:155], v207 offset:39936
	ds_read_b128 v[184:187], v168
	ds_read_b128 v[188:191], v168 offset:1024
	ds_read_b128 v[192:195], v168 offset:2048
	ds_read_b128 v[196:199], v168 offset:3072
	ds_read_b128 v[168:171], v180
	ds_read_b128 v[172:175], v180 offset:1024
	ds_read_b128 v[176:179], v180 offset:2048
	ds_read_b128 v[180:183], v180 offset:3072
	global_load_lds_dwordx4 v[242:243], off
	v_lshl_add_u64 v[240:241], v[240:241], 0, v[210:211]
	s_mov_b32 m0, s63
	s_nop 0
	global_load_lds_dwordx4 v[240:241], off
	s_waitcnt vmcnt(8)
	s_waitcnt lgkmcnt(0)
	s_barrier
	s_waitcnt lgkmcnt(0)
	v_mfma_f32_16x16x32_bf16 v[132:135], v[184:187], v[148:151], v[132:135]
	v_mfma_f32_16x16x32_bf16 v[132:135], v[188:191], v[164:167], v[132:135]
	v_mfma_f32_16x16x32_bf16 v[128:131], v[192:195], v[148:151], v[128:131]
	v_mfma_f32_16x16x32_bf16 v[128:131], v[196:199], v[164:167], v[128:131]
	v_mfma_f32_16x16x32_bf16 v[116:119], v[168:171], v[148:151], v[116:119]
	v_mfma_f32_16x16x32_bf16 v[116:119], v[172:175], v[164:167], v[116:119]
	v_mfma_f32_16x16x32_bf16 v[112:115], v[176:179], v[148:151], v[112:115]
	v_mfma_f32_16x16x32_bf16 v[112:115], v[180:183], v[164:167], v[112:115]
	v_mfma_f32_16x16x32_bf16 v[96:99], v[176:179], v[144:147], v[96:99]
	v_mfma_f32_16x16x32_bf16 v[96:99], v[180:183], v[160:163], v[96:99]
	v_mfma_f32_16x16x32_bf16 v[100:103], v[168:171], v[144:147], v[100:103]
	v_mfma_f32_16x16x32_bf16 v[100:103], v[172:175], v[160:163], v[100:103]
	v_mfma_f32_16x16x32_bf16 v[120:123], v[192:195], v[144:147], v[120:123]
	v_mfma_f32_16x16x32_bf16 v[120:123], v[196:199], v[160:163], v[120:123]
	v_mfma_f32_16x16x32_bf16 v[124:127], v[184:187], v[144:147], v[124:127]
	v_mfma_f32_16x16x32_bf16 v[124:127], v[188:191], v[160:163], v[124:127]
	v_mfma_f32_16x16x32_bf16 v[108:111], v[184:187], v[140:143], v[108:111]
	v_mfma_f32_16x16x32_bf16 v[108:111], v[188:191], v[156:159], v[108:111]
	v_mfma_f32_16x16x32_bf16 v[104:107], v[192:195], v[140:143], v[104:107]
	v_mfma_f32_16x16x32_bf16 v[104:107], v[196:199], v[156:159], v[104:107]
	v_mfma_f32_16x16x32_bf16 v[84:87], v[168:171], v[140:143], v[84:87]
	v_mfma_f32_16x16x32_bf16 v[84:87], v[172:175], v[156:159], v[84:87]
	v_mfma_f32_16x16x32_bf16 v[80:83], v[176:179], v[140:143], v[80:83]
	v_mfma_f32_16x16x32_bf16 v[80:83], v[180:183], v[156:159], v[80:83]
	v_mfma_f32_16x16x32_bf16 v[72:75], v[176:179], v[136:139], v[72:75]
	v_mfma_f32_16x16x32_bf16 v[72:75], v[180:183], v[152:155], v[72:75]
	v_mfma_f32_16x16x32_bf16 v[76:79], v[168:171], v[136:139], v[76:79]
	v_mfma_f32_16x16x32_bf16 v[76:79], v[172:175], v[152:155], v[76:79]
	v_mfma_f32_16x16x32_bf16 v[88:91], v[192:195], v[136:139], v[88:91]
	v_mfma_f32_16x16x32_bf16 v[88:91], v[196:199], v[152:155], v[88:91]
	v_mfma_f32_16x16x32_bf16 v[92:95], v[184:187], v[136:139], v[92:95]
	v_mfma_f32_16x16x32_bf16 v[92:95], v[188:191], v[152:155], v[92:95]
	s_barrier
	s_and_b64 vcc, exec, s[50:51]
	s_cbranch_vccnz .LBB0_375
	ds_read_b128 v[148:151], v207 offset:49152
	ds_read_b128 v[164:167], v207 offset:50176
	ds_read_b128 v[144:147], v207 offset:51200
	ds_read_b128 v[160:163], v207 offset:52224
	ds_read_b128 v[140:143], v207 offset:53248
	ds_read_b128 v[156:159], v207 offset:54272
	ds_read_b128 v[136:139], v207 offset:55296
	ds_read_b128 v[152:155], v207 offset:56320

.LBB0_559:
	v_add_u32_e32 v168, 0x10000, v240
	v_add_u32_e32 v180, 0x14000, v240
	v_lshl_add_u64 v[226:227], v[224:225], 0, s[64:65]
	s_add_i32 m0, s38, 0xc000
	s_waitcnt lgkmcnt(0)
	ds_read_b128 v[148:151], v239
	ds_read_b128 v[164:167], v239 offset:1024
	ds_read_b128 v[144:147], v239 offset:2048
	ds_read_b128 v[160:163], v239 offset:3072
	ds_read_b128 v[140:143], v239 offset:4096
	ds_read_b128 v[156:159], v239 offset:5120
	ds_read_b128 v[136:139], v239 offset:6144
	ds_read_b128 v[152:155], v239 offset:7168
	ds_read_b128 v[184:187], v168
	ds_read_b128 v[188:191], v168 offset:1024
	ds_read_b128 v[192:195], v168 offset:2048
	ds_read_b128 v[196:199], v168 offset:3072
	ds_read_b128 v[168:171], v180
	ds_read_b128 v[172:175], v180 offset:1024
	ds_read_b128 v[176:179], v180 offset:2048
	ds_read_b128 v[180:183], v180 offset:3072
	global_load_lds_dwordx4 v[226:227], off
	v_lshl_add_u64 v[226:227], v[222:223], 0, s[64:65]
	s_add_i32 m0, s38, 0xe000
	s_nop 0
	global_load_lds_dwordx4 v[226:227], off
	s_waitcnt vmcnt(8)
	s_waitcnt lgkmcnt(0)
	s_barrier
	s_waitcnt lgkmcnt(0)
	v_mfma_f32_16x16x32_bf16 v[132:135], v[184:187], v[148:151], v[132:135]
	v_mfma_f32_16x16x32_bf16 v[132:135], v[188:191], v[164:167], v[132:135]
	v_mfma_f32_16x16x32_bf16 v[128:131], v[192:195], v[148:151], v[128:131]
	v_mfma_f32_16x16x32_bf16 v[128:131], v[196:199], v[164:167], v[128:131]
	v_mfma_f32_16x16x32_bf16 v[124:127], v[168:171], v[148:151], v[124:127]
	v_mfma_f32_16x16x32_bf16 v[124:127], v[172:175], v[164:167], v[124:127]
	v_mfma_f32_16x16x32_bf16 v[120:123], v[176:179], v[148:151], v[120:123]
	v_mfma_f32_16x16x32_bf16 v[120:123], v[180:183], v[164:167], v[120:123]
	v_mfma_f32_16x16x32_bf16 v[104:107], v[176:179], v[144:147], v[104:107]
	v_mfma_f32_16x16x32_bf16 v[104:107], v[180:183], v[160:163], v[104:107]
	v_mfma_f32_16x16x32_bf16 v[108:111], v[168:171], v[144:147], v[108:111]
	v_mfma_f32_16x16x32_bf16 v[108:111], v[172:175], v[160:163], v[108:111]
	v_mfma_f32_16x16x32_bf16 v[112:115], v[192:195], v[144:147], v[112:115]
	v_mfma_f32_16x16x32_bf16 v[112:115], v[196:199], v[160:163], v[112:115]
	v_mfma_f32_16x16x32_bf16 v[116:119], v[184:187], v[144:147], v[116:119]
	v_mfma_f32_16x16x32_bf16 v[116:119], v[188:191], v[160:163], v[116:119]
	v_mfma_f32_16x16x32_bf16 v[100:103], v[184:187], v[140:143], v[100:103]
	v_mfma_f32_16x16x32_bf16 v[100:103], v[188:191], v[156:159], v[100:103]
	v_mfma_f32_16x16x32_bf16 v[96:99], v[192:195], v[140:143], v[96:99]
	v_mfma_f32_16x16x32_bf16 v[96:99], v[196:199], v[156:159], v[96:99]
	v_mfma_f32_16x16x32_bf16 v[92:95], v[168:171], v[140:143], v[92:95]
	v_mfma_f32_16x16x32_bf16 v[92:95], v[172:175], v[156:159], v[92:95]
	v_mfma_f32_16x16x32_bf16 v[88:91], v[176:179], v[140:143], v[88:91]
	v_mfma_f32_16x16x32_bf16 v[88:91], v[180:183], v[156:159], v[88:91]
	v_mfma_f32_16x16x32_bf16 v[72:75], v[176:179], v[136:139], v[72:75]
	v_mfma_f32_16x16x32_bf16 v[72:75], v[180:183], v[152:155], v[72:75]
	v_mfma_f32_16x16x32_bf16 v[76:79], v[168:171], v[136:139], v[76:79]
	v_mfma_f32_16x16x32_bf16 v[76:79], v[172:175], v[152:155], v[76:79]
	v_mfma_f32_16x16x32_bf16 v[80:83], v[192:195], v[136:139], v[80:83]
	v_mfma_f32_16x16x32_bf16 v[80:83], v[196:199], v[152:155], v[80:83]
	v_mfma_f32_16x16x32_bf16 v[84:87], v[184:187], v[136:139], v[84:87]
	v_mfma_f32_16x16x32_bf16 v[84:87], v[188:191], v[152:155], v[84:87]
	s_barrier
	v_cndmask_b32_e64 v204, 0, 1, s[62:63]
	v_cmp_ne_u32_e64 s[50:51], 1, v204
	s_andn2_b64 vcc, exec, s[62:63]
	s_cbranch_vccnz .LBB0_561
	ds_read_b128 v[148:151], v239 offset:16384
	ds_read_b128 v[164:167], v239 offset:17408
	ds_read_b128 v[144:147], v239 offset:18432
	ds_read_b128 v[160:163], v239 offset:19456
	ds_read_b128 v[140:143], v239 offset:20480
	ds_read_b128 v[156:159], v239 offset:21504
	ds_read_b128 v[136:139], v239 offset:22528
	ds_read_b128 v[152:155], v239 offset:23552
.LBB0_561:
	s_add_u32 s12, s60, s64
	s_addc_u32 s13, s61, s65
	s_add_u32 s14, s12, 0x100
	s_addc_u32 s15, s13, 0
	s_add_u32 s79, s26, s64
	s_addc_u32 s80, s27, s65
	s_cmpk_eq_i32 s64, 0x300
	s_cselect_b64 s[52:53], -1, 0
	s_and_b64 s[12:13], s[52:53], exec
	s_cselect_b32 s13, s17, s80
	s_cselect_b32 s12, s35, s79
	s_mov_b32 m0, s39
	s_cselect_b32 s15, s21, s15
	s_cselect_b32 s14, s33, s14
	v_lshl_add_u64 v[226:227], s[12:13], 0, v[4:5]
	s_add_u32 s80, s12, 0x20000
	global_load_lds_dwordx4 v[226:227], off
	v_lshl_add_u64 v[228:229], s[12:13], 0, v[208:209]
	s_mov_b32 m0, s40
	s_addc_u32 s81, s13, 0
	global_load_lds_dwordx4 v[228:229], off
	v_lshl_add_u64 v[230:231], s[80:81], 0, v[4:5]
	s_mov_b32 m0, s41
	v_lshl_add_u64 v[232:233], s[14:15], 0, v[208:209]
	global_load_lds_dwordx4 v[230:231], off
	v_lshl_add_u64 v[230:231], s[80:81], 0, v[208:209]
	s_mov_b32 m0, s47
	s_and_b64 vcc, exec, s[50:51]
	global_load_lds_dwordx4 v[230:231], off
	v_lshl_add_u64 v[230:231], s[14:15], 0, v[4:5]
	s_mov_b32 m0, s38
	s_nop 0
	global_load_lds_dwordx4 v[230:231], off
	s_mov_b32 m0, s59
	s_nop 0
	global_load_lds_dwordx4 v[232:233], off
	s_waitcnt vmcnt(8)
	s_waitcnt lgkmcnt(0)
	s_barrier
	s_cbranch_vccnz .LBB0_563
	s_waitcnt lgkmcnt(0)
	v_mfma_f32_16x16x32_bf16 v[68:71], v[184:187], v[148:151], v[68:71]
	v_mfma_f32_16x16x32_bf16 v[68:71], v[188:191], v[164:167], v[68:71]
	v_mfma_f32_16x16x32_bf16 v[64:67], v[192:195], v[148:151], v[64:67]
	v_mfma_f32_16x16x32_bf16 v[64:67], v[196:199], v[164:167], v[64:67]
	v_mfma_f32_16x16x32_bf16 v[60:63], v[168:171], v[148:151], v[60:63]
	v_mfma_f32_16x16x32_bf16 v[60:63], v[172:175], v[164:167], v[60:63]
	v_mfma_f32_16x16x32_bf16 v[56:59], v[176:179], v[148:151], v[56:59]
	v_mfma_f32_16x16x32_bf16 v[56:59], v[180:183], v[164:167], v[56:59]
	v_mfma_f32_16x16x32_bf16 v[40:43], v[176:179], v[144:147], v[40:43]
	v_mfma_f32_16x16x32_bf16 v[40:43], v[180:183], v[160:163], v[40:43]
	v_mfma_f32_16x16x32_bf16 v[44:47], v[168:171], v[144:147], v[44:47]
	v_mfma_f32_16x16x32_bf16 v[44:47], v[172:175], v[160:163], v[44:47]
	v_mfma_f32_16x16x32_bf16 v[48:51], v[192:195], v[144:147], v[48:51]
	v_mfma_f32_16x16x32_bf16 v[48:51], v[196:199], v[160:163], v[48:51]
	v_mfma_f32_16x16x32_bf16 v[52:55], v[184:187], v[144:147], v[52:55]
	v_mfma_f32_16x16x32_bf16 v[52:55], v[188:191], v[160:163], v[52:55]
	v_mfma_f32_16x16x32_bf16 v[36:39], v[184:187], v[140:143], v[36:39]
	v_mfma_f32_16x16x32_bf16 v[36:39], v[188:191], v[156:159], v[36:39]
	v_mfma_f32_16x16x32_bf16 v[32:35], v[192:195], v[140:143], v[32:35]
	v_mfma_f32_16x16x32_bf16 v[32:35], v[196:199], v[156:159], v[32:35]
	v_mfma_f32_16x16x32_bf16 v[28:31], v[168:171], v[140:143], v[28:31]
	v_mfma_f32_16x16x32_bf16 v[28:31], v[172:175], v[156:159], v[28:31]
	v_mfma_f32_16x16x32_bf16 v[24:27], v[176:179], v[140:143], v[24:27]
	v_mfma_f32_16x16x32_bf16 v[24:27], v[180:183], v[156:159], v[24:27]
	v_mfma_f32_16x16x32_bf16 v[8:11], v[176:179], v[136:139], v[8:11]
	v_mfma_f32_16x16x32_bf16 v[8:11], v[180:183], v[152:155], v[8:11]
	v_mfma_f32_16x16x32_bf16 v[12:15], v[168:171], v[136:139], v[12:15]
	v_mfma_f32_16x16x32_bf16 v[12:15], v[172:175], v[152:155], v[12:15]
	v_mfma_f32_16x16x32_bf16 v[16:19], v[192:195], v[136:139], v[16:19]
	v_mfma_f32_16x16x32_bf16 v[16:19], v[196:199], v[152:155], v[16:19]
	v_mfma_f32_16x16x32_bf16 v[20:23], v[184:187], v[136:139], v[20:23]
	v_mfma_f32_16x16x32_bf16 v[20:23], v[188:191], v[152:155], v[20:23]
.LBB0_563:
	s_barrier
	v_cndmask_b32_e64 v243, v221, 0, s[52:53]
	v_cndmask_b32_e64 v242, v220, v2, s[52:53]
	v_lshl_add_u64 v[242:243], s[14:15], 0, v[242:243]
	s_mov_b32 m0, s66
	v_add_u32_e32 v168, 0x18000, v240
	v_add_u32_e32 v180, 0x1c000, v240
	v_lshl_add_u64 v[204:205], v[242:243], 0, v[4:5]
	s_waitcnt lgkmcnt(0)
	ds_read_b128 v[148:151], v239 offset:32768
	ds_read_b128 v[164:167], v239 offset:33792
	ds_read_b128 v[144:147], v239 offset:34816
	ds_read_b128 v[160:163], v239 offset:35840
	ds_read_b128 v[140:143], v239 offset:36864
	ds_read_b128 v[156:159], v239 offset:37888
	ds_read_b128 v[136:139], v239 offset:38912
	ds_read_b128 v[152:155], v239 offset:39936
	ds_read_b128 v[184:187], v168
	ds_read_b128 v[188:191], v168 offset:1024
	ds_read_b128 v[192:195], v168 offset:2048
	ds_read_b128 v[196:199], v168 offset:3072
	ds_read_b128 v[168:171], v180
	ds_read_b128 v[172:175], v180 offset:1024
	ds_read_b128 v[176:179], v180 offset:2048
	ds_read_b128 v[180:183], v180 offset:3072
	global_load_lds_dwordx4 v[204:205], off
	v_lshl_add_u64 v[204:205], v[242:243], 0, v[208:209]
	s_mov_b32 m0, s67
	s_nop 0
	global_load_lds_dwordx4 v[204:205], off
	s_waitcnt vmcnt(8)
	s_waitcnt lgkmcnt(0)
	s_barrier
	s_waitcnt lgkmcnt(0)
	v_mfma_f32_16x16x32_bf16 v[132:135], v[184:187], v[148:151], v[132:135]
	v_mfma_f32_16x16x32_bf16 v[132:135], v[188:191], v[164:167], v[132:135]
	v_mfma_f32_16x16x32_bf16 v[128:131], v[192:195], v[148:151], v[128:131]
	v_mfma_f32_16x16x32_bf16 v[128:131], v[196:199], v[164:167], v[128:131]
	v_mfma_f32_16x16x32_bf16 v[124:127], v[168:171], v[148:151], v[124:127]
	v_mfma_f32_16x16x32_bf16 v[124:127], v[172:175], v[164:167], v[124:127]
	v_mfma_f32_16x16x32_bf16 v[120:123], v[176:179], v[148:151], v[120:123]
	v_mfma_f32_16x16x32_bf16 v[120:123], v[180:183], v[164:167], v[120:123]
	v_mfma_f32_16x16x32_bf16 v[104:107], v[176:179], v[144:147], v[104:107]
	v_mfma_f32_16x16x32_bf16 v[104:107], v[180:183], v[160:163], v[104:107]
	v_mfma_f32_16x16x32_bf16 v[108:111], v[168:171], v[144:147], v[108:111]
	v_mfma_f32_16x16x32_bf16 v[108:111], v[172:175], v[160:163], v[108:111]
	v_mfma_f32_16x16x32_bf16 v[112:115], v[192:195], v[144:147], v[112:115]
	v_mfma_f32_16x16x32_bf16 v[112:115], v[196:199], v[160:163], v[112:115]
	v_mfma_f32_16x16x32_bf16 v[116:119], v[184:187], v[144:147], v[116:119]
	v_mfma_f32_16x16x32_bf16 v[116:119], v[188:191], v[160:163], v[116:119]
	v_mfma_f32_16x16x32_bf16 v[100:103], v[184:187], v[140:143], v[100:103]
	v_mfma_f32_16x16x32_bf16 v[100:103], v[188:191], v[156:159], v[100:103]
	v_mfma_f32_16x16x32_bf16 v[96:99], v[192:195], v[140:143], v[96:99]
	v_mfma_f32_16x16x32_bf16 v[96:99], v[196:199], v[156:159], v[96:99]
	v_mfma_f32_16x16x32_bf16 v[92:95], v[168:171], v[140:143], v[92:95]
	v_mfma_f32_16x16x32_bf16 v[92:95], v[172:175], v[156:159], v[92:95]
	v_mfma_f32_16x16x32_bf16 v[88:91], v[176:179], v[140:143], v[88:91]
	v_mfma_f32_16x16x32_bf16 v[88:91], v[180:183], v[156:159], v[88:91]
	v_mfma_f32_16x16x32_bf16 v[72:75], v[176:179], v[136:139], v[72:75]
	v_mfma_f32_16x16x32_bf16 v[72:75], v[180:183], v[152:155], v[72:75]
	v_mfma_f32_16x16x32_bf16 v[76:79], v[168:171], v[136:139], v[76:79]
	v_mfma_f32_16x16x32_bf16 v[76:79], v[172:175], v[152:155], v[76:79]
	v_mfma_f32_16x16x32_bf16 v[80:83], v[192:195], v[136:139], v[80:83]
	v_mfma_f32_16x16x32_bf16 v[80:83], v[196:199], v[152:155], v[80:83]
	v_mfma_f32_16x16x32_bf16 v[84:87], v[184:187], v[136:139], v[84:87]
	v_mfma_f32_16x16x32_bf16 v[84:87], v[188:191], v[152:155], v[84:87]
	s_barrier
	s_and_b64 vcc, exec, s[50:51]
	s_cbranch_vccnz .LBB0_565
	ds_read_b128 v[148:151], v239 offset:49152
	ds_read_b128 v[164:167], v239 offset:50176
	ds_read_b128 v[144:147], v239 offset:51200
	ds_read_b128 v[160:163], v239 offset:52224
	ds_read_b128 v[140:143], v239 offset:53248
	ds_read_b128 v[156:159], v239 offset:54272
	ds_read_b128 v[136:139], v239 offset:55296
	ds_read_b128 v[152:155], v239 offset:56320
.LBB0_565:
	s_mov_b32 m0, s70
	v_lshl_add_u64 v[204:205], v[226:227], 0, s[0:1]
	s_add_u32 s12, s12, 0x20080
	global_load_lds_dwordx4 v[204:205], off
	v_lshl_add_u64 v[204:205], v[228:229], 0, s[0:1]
	s_mov_b32 m0, s71
	s_addc_u32 s13, s13, 0
	global_load_lds_dwordx4 v[204:205], off
	v_lshl_add_u64 v[204:205], s[12:13], 0, v[4:5]
	s_mov_b32 m0, s74
	s_and_b64 vcc, exec, s[50:51]
	global_load_lds_dwordx4 v[204:205], off
	v_lshl_add_u64 v[204:205], s[12:13], 0, v[208:209]
	s_mov_b32 m0, s75
	s_nop 0
	global_load_lds_dwordx4 v[204:205], off
	v_lshl_add_u64 v[204:205], v[230:231], 0, s[0:1]
	s_mov_b32 m0, s72
	s_nop 0
	global_load_lds_dwordx4 v[204:205], off
	v_lshl_add_u64 v[204:205], v[232:233], 0, s[0:1]
	s_mov_b32 m0, s73
	s_nop 0
	global_load_lds_dwordx4 v[204:205], off
	s_waitcnt vmcnt(8)
	s_waitcnt lgkmcnt(0)
	s_barrier
	s_cbranch_vccnz .LBB0_558
	s_waitcnt lgkmcnt(0)
	v_mfma_f32_16x16x32_bf16 v[68:71], v[184:187], v[148:151], v[68:71]
	v_mfma_f32_16x16x32_bf16 v[68:71], v[188:191], v[164:167], v[68:71]
	v_mfma_f32_16x16x32_bf16 v[64:67], v[192:195], v[148:151], v[64:67]
	v_mfma_f32_16x16x32_bf16 v[64:67], v[196:199], v[164:167], v[64:67]
	v_mfma_f32_16x16x32_bf16 v[60:63], v[168:171], v[148:151], v[60:63]
	v_mfma_f32_16x16x32_bf16 v[60:63], v[172:175], v[164:167], v[60:63]
	v_mfma_f32_16x16x32_bf16 v[56:59], v[176:179], v[148:151], v[56:59]
	v_mfma_f32_16x16x32_bf16 v[56:59], v[180:183], v[164:167], v[56:59]
	v_mfma_f32_16x16x32_bf16 v[40:43], v[176:179], v[144:147], v[40:43]
	v_mfma_f32_16x16x32_bf16 v[40:43], v[180:183], v[160:163], v[40:43]
	v_mfma_f32_16x16x32_bf16 v[44:47], v[168:171], v[144:147], v[44:47]
	v_mfma_f32_16x16x32_bf16 v[44:47], v[172:175], v[160:163], v[44:47]
	v_mfma_f32_16x16x32_bf16 v[48:51], v[192:195], v[144:147], v[48:51]
	v_mfma_f32_16x16x32_bf16 v[48:51], v[196:199], v[160:163], v[48:51]
	v_mfma_f32_16x16x32_bf16 v[52:55], v[184:187], v[144:147], v[52:55]
	v_mfma_f32_16x16x32_bf16 v[52:55], v[188:191], v[160:163], v[52:55]
	v_mfma_f32_16x16x32_bf16 v[36:39], v[184:187], v[140:143], v[36:39]
	v_mfma_f32_16x16x32_bf16 v[36:39], v[188:191], v[156:159], v[36:39]
	v_mfma_f32_16x16x32_bf16 v[32:35], v[192:195], v[140:143], v[32:35]
	v_mfma_f32_16x16x32_bf16 v[32:35], v[196:199], v[156:159], v[32:35]
	v_mfma_f32_16x16x32_bf16 v[28:31], v[168:171], v[140:143], v[28:31]
	v_mfma_f32_16x16x32_bf16 v[28:31], v[172:175], v[156:159], v[28:31]
	v_mfma_f32_16x16x32_bf16 v[24:27], v[176:179], v[140:143], v[24:27]
	v_mfma_f32_16x16x32_bf16 v[24:27], v[180:183], v[156:159], v[24:27]
	v_mfma_f32_16x16x32_bf16 v[8:11], v[176:179], v[136:139], v[8:11]
	v_mfma_f32_16x16x32_bf16 v[8:11], v[180:183], v[152:155], v[8:11]
	v_mfma_f32_16x16x32_bf16 v[12:15], v[168:171], v[136:139], v[12:15]
	v_mfma_f32_16x16x32_bf16 v[12:15], v[172:175], v[152:155], v[12:15]
	v_mfma_f32_16x16x32_bf16 v[16:19], v[192:195], v[136:139], v[16:19]
	v_mfma_f32_16x16x32_bf16 v[16:19], v[196:199], v[152:155], v[16:19]
	v_mfma_f32_16x16x32_bf16 v[20:23], v[184:187], v[136:139], v[20:23]
	v_mfma_f32_16x16x32_bf16 v[20:23], v[188:191], v[152:155], v[20:23]
	s_branch .LBB0_558

.LBB0_620:
	s_add_u32 s12, s42, 0xfffe0080
	s_addc_u32 s13, s43, -1
	s_cmp_eq_u32 s57, 4
	s_cselect_b32 s15, s17, s13
	s_cselect_b32 s14, s33, s12
	s_cselect_b32 s13, s11, s27
	s_cselect_b32 s12, s37, s26
	s_add_i32 s58, 0, 0x10000
	v_add_u32_e32 v136, s58, v1
	s_add_i32 s60, 0, 0x14000
	ds_read_b128 v[150:153], v7
	ds_read_b128 v[154:157], v7 offset:1024
	ds_read_b128 v[158:161], v7 offset:2048
	ds_read_b128 v[162:165], v7 offset:3072
	ds_read_b128 v[166:169], v7 offset:4096
	ds_read_b128 v[170:173], v7 offset:5120
	ds_read_b128 v[174:177], v7 offset:6144
	ds_read_b128 v[178:181], v7 offset:7168
	ds_read_b128 v[182:185], v136
	ds_read_b128 v[186:189], v136 offset:1024
	ds_read_b128 v[190:193], v136 offset:2048
	ds_read_b128 v[194:197], v136 offset:3072
	v_add_u32_e32 v136, s60, v1
	ds_read_b128 v[208:211], v136
	ds_read_b128 v[212:215], v136 offset:1024
	ds_read_b128 v[216:219], v136 offset:2048
	ds_read_b128 v[220:223], v136 offset:3072
	v_lshl_add_u64 v[136:137], s[42:43], 0, v[146:147]
	s_add_i32 m0, s38, 0xc000
	s_nop 0
	global_load_lds_dwordx4 v[136:137], off
	v_lshl_add_u64 v[136:137], s[42:43], 0, v[148:149]
	s_add_i32 m0, s38, 0xe000
	s_nop 0
	global_load_lds_dwordx4 v[136:137], off
	s_waitcnt vmcnt(8)
	s_waitcnt lgkmcnt(0)
	s_barrier
	s_waitcnt lgkmcnt(0)
	v_mfma_f32_16x16x32_bf16 v[132:135], v[182:185], v[150:153], v[132:135]
	v_mfma_f32_16x16x32_bf16 v[132:135], v[186:189], v[154:157], v[132:135]
	v_mfma_f32_16x16x32_bf16 v[128:131], v[190:193], v[150:153], v[128:131]
	v_mfma_f32_16x16x32_bf16 v[128:131], v[194:197], v[154:157], v[128:131]
	v_mfma_f32_16x16x32_bf16 v[112:115], v[208:211], v[150:153], v[112:115]
	v_mfma_f32_16x16x32_bf16 v[112:115], v[212:215], v[154:157], v[112:115]
	v_mfma_f32_16x16x32_bf16 v[104:107], v[216:219], v[150:153], v[104:107]
	v_mfma_f32_16x16x32_bf16 v[104:107], v[220:223], v[154:157], v[104:107]
	v_mfma_f32_16x16x32_bf16 v[88:91], v[216:219], v[158:161], v[88:91]
	v_mfma_f32_16x16x32_bf16 v[88:91], v[220:223], v[162:165], v[88:91]
	v_mfma_f32_16x16x32_bf16 v[96:99], v[208:211], v[158:161], v[96:99]
	v_mfma_f32_16x16x32_bf16 v[96:99], v[212:215], v[162:165], v[96:99]
	v_mfma_f32_16x16x32_bf16 v[120:123], v[190:193], v[158:161], v[120:123]
	v_mfma_f32_16x16x32_bf16 v[120:123], v[194:197], v[162:165], v[120:123]
	v_mfma_f32_16x16x32_bf16 v[124:127], v[182:185], v[158:161], v[124:127]
	v_mfma_f32_16x16x32_bf16 v[124:127], v[186:189], v[162:165], v[124:127]
	v_mfma_f32_16x16x32_bf16 v[116:119], v[182:185], v[166:169], v[116:119]
	v_mfma_f32_16x16x32_bf16 v[116:119], v[186:189], v[170:173], v[116:119]
	v_mfma_f32_16x16x32_bf16 v[108:111], v[190:193], v[166:169], v[108:111]
	v_mfma_f32_16x16x32_bf16 v[108:111], v[194:197], v[170:173], v[108:111]
	v_mfma_f32_16x16x32_bf16 v[84:87], v[208:211], v[166:169], v[84:87]
	v_mfma_f32_16x16x32_bf16 v[84:87], v[212:215], v[170:173], v[84:87]
	v_mfma_f32_16x16x32_bf16 v[80:83], v[216:219], v[166:169], v[80:83]
	v_mfma_f32_16x16x32_bf16 v[80:83], v[220:223], v[170:173], v[80:83]
	v_mfma_f32_16x16x32_bf16 v[72:75], v[216:219], v[174:177], v[72:75]
	v_mfma_f32_16x16x32_bf16 v[72:75], v[220:223], v[178:181], v[72:75]
	v_mfma_f32_16x16x32_bf16 v[76:79], v[208:211], v[174:177], v[76:79]
	v_mfma_f32_16x16x32_bf16 v[76:79], v[212:215], v[178:181], v[76:79]
	v_mfma_f32_16x16x32_bf16 v[92:95], v[190:193], v[174:177], v[92:95]
	v_mfma_f32_16x16x32_bf16 v[92:95], v[194:197], v[178:181], v[92:95]
	v_mfma_f32_16x16x32_bf16 v[100:103], v[182:185], v[174:177], v[100:103]
	v_mfma_f32_16x16x32_bf16 v[100:103], v[186:189], v[178:181], v[100:103]
	s_barrier
	s_add_i32 s58, s58, s35
	v_lshl_add_u64 v[136:137], s[12:13], 0, v[2:3]
	s_mov_b32 m0, s58
	ds_read_b128 v[150:153], v7 offset:16384
	ds_read_b128 v[154:157], v7 offset:17408
	ds_read_b128 v[158:161], v7 offset:18432
	ds_read_b128 v[162:165], v7 offset:19456
	ds_read_b128 v[166:169], v7 offset:20480
	ds_read_b128 v[170:173], v7 offset:21504
	ds_read_b128 v[174:177], v7 offset:22528
	ds_read_b128 v[178:181], v7 offset:23552
	global_load_lds_dwordx4 v[136:137], off
	s_add_i32 m0, s58, 0x2000
	s_add_u32 s58, s12, 0x20000
	v_lshl_add_u64 v[198:199], s[12:13], 0, v[4:5]
	s_addc_u32 s59, s13, 0
	s_add_i32 s60, s60, s35
	global_load_lds_dwordx4 v[198:199], off
	v_lshl_add_u64 v[204:205], s[58:59], 0, v[2:3]
	s_mov_b32 m0, s60
	v_lshl_add_u64 v[224:225], s[14:15], 0, v[138:139]
	global_load_lds_dwordx4 v[204:205], off
	v_lshl_add_u64 v[204:205], s[58:59], 0, v[4:5]
	s_add_i32 m0, s60, 0x2000
	s_nop 0
	global_load_lds_dwordx4 v[204:205], off
	v_lshl_add_u64 v[204:205], s[14:15], 0, v[140:141]
	s_mov_b32 m0, s38
	s_nop 0
	global_load_lds_dwordx4 v[204:205], off
	s_mov_b32 m0, s39
	s_nop 0
	global_load_lds_dwordx4 v[224:225], off
	s_waitcnt vmcnt(8)
	s_waitcnt lgkmcnt(0)
	s_barrier
	s_waitcnt lgkmcnt(0)
	v_mfma_f32_16x16x32_bf16 v[68:71], v[182:185], v[150:153], v[68:71]
	v_mfma_f32_16x16x32_bf16 v[68:71], v[186:189], v[154:157], v[68:71]
	v_mfma_f32_16x16x32_bf16 v[64:67], v[190:193], v[150:153], v[64:67]
	v_mfma_f32_16x16x32_bf16 v[64:67], v[194:197], v[154:157], v[64:67]
	v_mfma_f32_16x16x32_bf16 v[48:51], v[208:211], v[150:153], v[48:51]
	v_mfma_f32_16x16x32_bf16 v[48:51], v[212:215], v[154:157], v[48:51]
	v_mfma_f32_16x16x32_bf16 v[40:43], v[216:219], v[150:153], v[40:43]
	v_mfma_f32_16x16x32_bf16 v[40:43], v[220:223], v[154:157], v[40:43]
	v_mfma_f32_16x16x32_bf16 v[24:27], v[216:219], v[158:161], v[24:27]
	v_mfma_f32_16x16x32_bf16 v[24:27], v[220:223], v[162:165], v[24:27]
	v_mfma_f32_16x16x32_bf16 v[32:35], v[208:211], v[158:161], v[32:35]
	v_mfma_f32_16x16x32_bf16 v[32:35], v[212:215], v[162:165], v[32:35]
	v_mfma_f32_16x16x32_bf16 v[56:59], v[190:193], v[158:161], v[56:59]
	v_mfma_f32_16x16x32_bf16 v[56:59], v[194:197], v[162:165], v[56:59]
	v_mfma_f32_16x16x32_bf16 v[60:63], v[182:185], v[158:161], v[60:63]
	v_mfma_f32_16x16x32_bf16 v[60:63], v[186:189], v[162:165], v[60:63]
	v_mfma_f32_16x16x32_bf16 v[52:55], v[182:185], v[166:169], v[52:55]
	v_mfma_f32_16x16x32_bf16 v[52:55], v[186:189], v[170:173], v[52:55]
	v_mfma_f32_16x16x32_bf16 v[44:47], v[190:193], v[166:169], v[44:47]
	v_mfma_f32_16x16x32_bf16 v[44:47], v[194:197], v[170:173], v[44:47]
	v_mfma_f32_16x16x32_bf16 v[20:23], v[208:211], v[166:169], v[20:23]
	v_mfma_f32_16x16x32_bf16 v[20:23], v[212:215], v[170:173], v[20:23]
	v_mfma_f32_16x16x32_bf16 v[16:19], v[216:219], v[166:169], v[16:19]
	v_mfma_f32_16x16x32_bf16 v[16:19], v[220:223], v[170:173], v[16:19]
	v_mfma_f32_16x16x32_bf16 v[8:11], v[216:219], v[174:177], v[8:11]
	v_mfma_f32_16x16x32_bf16 v[8:11], v[220:223], v[178:181], v[8:11]
	v_mfma_f32_16x16x32_bf16 v[12:15], v[208:211], v[174:177], v[12:15]
	v_mfma_f32_16x16x32_bf16 v[12:15], v[212:215], v[178:181], v[12:15]
	v_mfma_f32_16x16x32_bf16 v[28:31], v[190:193], v[174:177], v[28:31]
	v_mfma_f32_16x16x32_bf16 v[28:31], v[194:197], v[178:181], v[28:31]
	v_mfma_f32_16x16x32_bf16 v[36:39], v[182:185], v[174:177], v[36:39]
	v_mfma_f32_16x16x32_bf16 v[36:39], v[186:189], v[178:181], v[36:39]
	s_barrier
	s_add_i32 s58, 0, 0x18000
	s_add_i32 s59, 0, 0x1c000
	s_add_u32 s14, s14, 0x20000
	s_addc_u32 s15, s15, 0
	s_mov_b32 m0, s40
	v_add_u32_e32 v194, s58, v1
	v_add_u32_e32 v207, s59, v1
	v_lshl_add_u64 v[226:227], s[14:15], 0, v[140:141]
	ds_read_b128 v[150:153], v7 offset:32768
	ds_read_b128 v[154:157], v7 offset:33792
	ds_read_b128 v[158:161], v7 offset:34816
	ds_read_b128 v[162:165], v7 offset:35840
	ds_read_b128 v[166:169], v7 offset:36864
	ds_read_b128 v[170:173], v7 offset:37888
	ds_read_b128 v[174:177], v7 offset:38912
	ds_read_b128 v[178:181], v7 offset:39936
	ds_read_b128 v[182:185], v194
	ds_read_b128 v[186:189], v194 offset:1024
	ds_read_b128 v[190:193], v194 offset:2048
	ds_read_b128 v[194:197], v194 offset:3072
	ds_read_b128 v[208:211], v207
	ds_read_b128 v[212:215], v207 offset:1024
	ds_read_b128 v[216:219], v207 offset:2048
	ds_read_b128 v[220:223], v207 offset:3072
	global_load_lds_dwordx4 v[226:227], off
	v_lshl_add_u64 v[226:227], s[14:15], 0, v[138:139]
	s_mov_b32 m0, s41
	s_nop 0
	global_load_lds_dwordx4 v[226:227], off
	s_waitcnt vmcnt(8)
	s_waitcnt lgkmcnt(0)
	s_barrier
	s_waitcnt lgkmcnt(0)
	v_mfma_f32_16x16x32_bf16 v[132:135], v[182:185], v[150:153], v[132:135]
	v_mfma_f32_16x16x32_bf16 v[132:135], v[186:189], v[154:157], v[132:135]
	v_mfma_f32_16x16x32_bf16 v[128:131], v[190:193], v[150:153], v[128:131]
	v_mfma_f32_16x16x32_bf16 v[128:131], v[194:197], v[154:157], v[128:131]
	v_mfma_f32_16x16x32_bf16 v[112:115], v[208:211], v[150:153], v[112:115]
	v_mfma_f32_16x16x32_bf16 v[112:115], v[212:215], v[154:157], v[112:115]
	v_mfma_f32_16x16x32_bf16 v[104:107], v[216:219], v[150:153], v[104:107]
	v_mfma_f32_16x16x32_bf16 v[104:107], v[220:223], v[154:157], v[104:107]
	v_mfma_f32_16x16x32_bf16 v[88:91], v[216:219], v[158:161], v[88:91]
	v_mfma_f32_16x16x32_bf16 v[88:91], v[220:223], v[162:165], v[88:91]
	v_mfma_f32_16x16x32_bf16 v[96:99], v[208:211], v[158:161], v[96:99]
	v_mfma_f32_16x16x32_bf16 v[96:99], v[212:215], v[162:165], v[96:99]
	v_mfma_f32_16x16x32_bf16 v[120:123], v[190:193], v[158:161], v[120:123]
	v_mfma_f32_16x16x32_bf16 v[120:123], v[194:197], v[162:165], v[120:123]
	v_mfma_f32_16x16x32_bf16 v[124:127], v[182:185], v[158:161], v[124:127]
	v_mfma_f32_16x16x32_bf16 v[124:127], v[186:189], v[162:165], v[124:127]
	v_mfma_f32_16x16x32_bf16 v[116:119], v[182:185], v[166:169], v[116:119]
	v_mfma_f32_16x16x32_bf16 v[116:119], v[186:189], v[170:173], v[116:119]
	v_mfma_f32_16x16x32_bf16 v[108:111], v[190:193], v[166:169], v[108:111]
	v_mfma_f32_16x16x32_bf16 v[108:111], v[194:197], v[170:173], v[108:111]
	v_mfma_f32_16x16x32_bf16 v[84:87], v[208:211], v[166:169], v[84:87]
	v_mfma_f32_16x16x32_bf16 v[84:87], v[212:215], v[170:173], v[84:87]
	v_mfma_f32_16x16x32_bf16 v[80:83], v[216:219], v[166:169], v[80:83]
	v_mfma_f32_16x16x32_bf16 v[80:83], v[220:223], v[170:173], v[80:83]
	v_mfma_f32_16x16x32_bf16 v[72:75], v[216:219], v[174:177], v[72:75]
	v_mfma_f32_16x16x32_bf16 v[72:75], v[220:223], v[178:181], v[72:75]
	v_mfma_f32_16x16x32_bf16 v[76:79], v[208:211], v[174:177], v[76:79]
	v_mfma_f32_16x16x32_bf16 v[76:79], v[212:215], v[178:181], v[76:79]
	v_mfma_f32_16x16x32_bf16 v[92:95], v[190:193], v[174:177], v[92:95]
	v_mfma_f32_16x16x32_bf16 v[92:95], v[194:197], v[178:181], v[92:95]
	v_mfma_f32_16x16x32_bf16 v[100:103], v[182:185], v[174:177], v[100:103]
	v_mfma_f32_16x16x32_bf16 v[100:103], v[186:189], v[178:181], v[100:103]
	s_barrier
	s_add_i32 s14, s58, s35
	v_lshl_add_u64 v[136:137], v[136:137], 0, s[0:1]
	s_mov_b32 m0, s14
	ds_read_b128 v[150:153], v7 offset:49152
	ds_read_b128 v[154:157], v7 offset:50176
	ds_read_b128 v[158:161], v7 offset:51200
	ds_read_b128 v[162:165], v7 offset:52224
	ds_read_b128 v[166:169], v7 offset:53248
	ds_read_b128 v[170:173], v7 offset:54272
	ds_read_b128 v[174:177], v7 offset:55296
	ds_read_b128 v[178:181], v7 offset:56320
	global_load_lds_dwordx4 v[136:137], off
	s_add_i32 m0, s14, 0x2000
	s_add_u32 s12, s12, 0x20080
	v_lshl_add_u64 v[136:137], v[198:199], 0, s[0:1]
	s_addc_u32 s13, s13, 0
	s_add_i32 s14, s59, s35
	global_load_lds_dwordx4 v[136:137], off
	v_lshl_add_u64 v[136:137], s[12:13], 0, v[2:3]
	s_mov_b32 m0, s14
	s_nop 0
	global_load_lds_dwordx4 v[136:137], off
	v_lshl_add_u64 v[136:137], s[12:13], 0, v[4:5]
	s_add_i32 m0, s14, 0x2000
	s_nop 0
	global_load_lds_dwordx4 v[136:137], off
	v_lshl_add_u64 v[136:137], v[204:205], 0, s[0:1]
	s_mov_b32 m0, s49
	s_nop 0
	global_load_lds_dwordx4 v[136:137], off
	v_lshl_add_u64 v[136:137], v[224:225], 0, s[0:1]
	s_mov_b32 m0, s52
	s_nop 0
	global_load_lds_dwordx4 v[136:137], off
	s_waitcnt vmcnt(8)
	s_waitcnt lgkmcnt(0)
	s_barrier
	s_waitcnt lgkmcnt(0)
	v_mfma_f32_16x16x32_bf16 v[68:71], v[182:185], v[150:153], v[68:71]
	v_mfma_f32_16x16x32_bf16 v[68:71], v[186:189], v[154:157], v[68:71]
	v_mfma_f32_16x16x32_bf16 v[64:67], v[190:193], v[150:153], v[64:67]
	v_mfma_f32_16x16x32_bf16 v[64:67], v[194:197], v[154:157], v[64:67]
	v_mfma_f32_16x16x32_bf16 v[48:51], v[208:211], v[150:153], v[48:51]
	v_mfma_f32_16x16x32_bf16 v[48:51], v[212:215], v[154:157], v[48:51]
	v_mfma_f32_16x16x32_bf16 v[40:43], v[216:219], v[150:153], v[40:43]
	v_mfma_f32_16x16x32_bf16 v[40:43], v[220:223], v[154:157], v[40:43]
	v_mfma_f32_16x16x32_bf16 v[24:27], v[216:219], v[158:161], v[24:27]
	v_mfma_f32_16x16x32_bf16 v[24:27], v[220:223], v[162:165], v[24:27]
	v_mfma_f32_16x16x32_bf16 v[32:35], v[208:211], v[158:161], v[32:35]
	v_mfma_f32_16x16x32_bf16 v[32:35], v[212:215], v[162:165], v[32:35]
	v_mfma_f32_16x16x32_bf16 v[56:59], v[190:193], v[158:161], v[56:59]
	v_mfma_f32_16x16x32_bf16 v[56:59], v[194:197], v[162:165], v[56:59]
	v_mfma_f32_16x16x32_bf16 v[60:63], v[182:185], v[158:161], v[60:63]
	v_mfma_f32_16x16x32_bf16 v[60:63], v[186:189], v[162:165], v[60:63]
	v_mfma_f32_16x16x32_bf16 v[52:55], v[182:185], v[166:169], v[52:55]
	v_mfma_f32_16x16x32_bf16 v[52:55], v[186:189], v[170:173], v[52:55]
	v_mfma_f32_16x16x32_bf16 v[44:47], v[190:193], v[166:169], v[44:47]
	v_mfma_f32_16x16x32_bf16 v[44:47], v[194:197], v[170:173], v[44:47]
	v_mfma_f32_16x16x32_bf16 v[20:23], v[208:211], v[166:169], v[20:23]
	v_mfma_f32_16x16x32_bf16 v[20:23], v[212:215], v[170:173], v[20:23]
	v_mfma_f32_16x16x32_bf16 v[16:19], v[216:219], v[166:169], v[16:19]
	v_mfma_f32_16x16x32_bf16 v[16:19], v[220:223], v[170:173], v[16:19]
	v_mfma_f32_16x16x32_bf16 v[8:11], v[216:219], v[174:177], v[8:11]
	v_mfma_f32_16x16x32_bf16 v[8:11], v[220:223], v[178:181], v[8:11]
	v_mfma_f32_16x16x32_bf16 v[12:15], v[208:211], v[174:177], v[12:15]
	v_mfma_f32_16x16x32_bf16 v[12:15], v[212:215], v[178:181], v[12:15]
	v_mfma_f32_16x16x32_bf16 v[28:31], v[190:193], v[174:177], v[28:31]
	v_mfma_f32_16x16x32_bf16 v[28:31], v[194:197], v[178:181], v[28:31]
	v_mfma_f32_16x16x32_bf16 v[36:39], v[182:185], v[174:177], v[36:39]
	v_mfma_f32_16x16x32_bf16 v[36:39], v[186:189], v[178:181], v[36:39]
	s_barrier
	s_add_i32 s57, s57, 2
	s_add_u32 s42, s42, 0x100
	s_addc_u32 s43, s43, 0
	s_add_u32 s26, s26, 0x100
	s_addc_u32 s27, s27, 0
	s_cmp_gt_u32 s57, 5
	s_cbranch_scc0 .LBB0_620
	s_and_b64 vcc, exec, s[6:7]
	s_cbranch_vccz .LBB0_623
	s_barrier

.LBB0_986:
	s_add_u32 s12, s44, 0xfff80080
	s_addc_u32 s13, s45, -1
	s_cmp_eq_u32 s50, 28
	s_cselect_b32 s15, s18, s13
	s_cselect_b32 s14, s19, s12
	s_cselect_b32 s13, s17, s43
	s_cselect_b32 s12, s21, s33
	s_add_i32 s51, 0, 0x10000
	v_add_u32_e32 v2, s51, v7
	s_add_i32 s63, 0, 0x14000
	ds_read_b128 v[150:153], v155
	ds_read_b128 v[156:159], v155 offset:1024
	ds_read_b128 v[160:163], v155 offset:2048
	ds_read_b128 v[164:167], v155 offset:3072
	ds_read_b128 v[168:171], v155 offset:4096
	ds_read_b128 v[172:175], v155 offset:5120
	ds_read_b128 v[176:179], v155 offset:6144
	ds_read_b128 v[180:183], v155 offset:7168
	ds_read_b128 v[184:187], v2
	ds_read_b128 v[188:191], v2 offset:1024
	ds_read_b128 v[192:195], v2 offset:2048
	ds_read_b128 v[196:199], v2 offset:3072
	v_add_u32_e32 v2, s63, v7
	v_lshl_add_u64 v[224:225], s[44:45], 0, v[146:147]
	s_add_i32 m0, s39, 0xc000
	ds_read_b128 v[208:211], v2
	ds_read_b128 v[212:215], v2 offset:1024
	ds_read_b128 v[216:219], v2 offset:2048
	ds_read_b128 v[220:223], v2 offset:3072
	global_load_lds_dwordx4 v[224:225], off
	v_lshl_add_u64 v[224:225], s[44:45], 0, v[148:149]
	s_add_i32 m0, s39, 0xe000
	s_nop 0
	global_load_lds_dwordx4 v[224:225], off
	s_waitcnt vmcnt(8)
	s_waitcnt lgkmcnt(0)
	s_barrier
	s_waitcnt lgkmcnt(0)
	v_mfma_f32_16x16x32_bf16 v[132:135], v[184:187], v[150:153], v[132:135]
	v_mfma_f32_16x16x32_bf16 v[132:135], v[188:191], v[156:159], v[132:135]
	v_mfma_f32_16x16x32_bf16 v[128:131], v[192:195], v[150:153], v[128:131]
	v_mfma_f32_16x16x32_bf16 v[128:131], v[196:199], v[156:159], v[128:131]
	v_mfma_f32_16x16x32_bf16 v[124:127], v[208:211], v[150:153], v[124:127]
	v_mfma_f32_16x16x32_bf16 v[124:127], v[212:215], v[156:159], v[124:127]
	v_mfma_f32_16x16x32_bf16 v[120:123], v[216:219], v[150:153], v[120:123]
	v_mfma_f32_16x16x32_bf16 v[120:123], v[220:223], v[156:159], v[120:123]
	v_mfma_f32_16x16x32_bf16 v[104:107], v[216:219], v[160:163], v[104:107]
	v_mfma_f32_16x16x32_bf16 v[104:107], v[220:223], v[164:167], v[104:107]
	v_mfma_f32_16x16x32_bf16 v[108:111], v[208:211], v[160:163], v[108:111]
	v_mfma_f32_16x16x32_bf16 v[108:111], v[212:215], v[164:167], v[108:111]
	v_mfma_f32_16x16x32_bf16 v[112:115], v[192:195], v[160:163], v[112:115]
	v_mfma_f32_16x16x32_bf16 v[112:115], v[196:199], v[164:167], v[112:115]
	v_mfma_f32_16x16x32_bf16 v[116:119], v[184:187], v[160:163], v[116:119]
	v_mfma_f32_16x16x32_bf16 v[116:119], v[188:191], v[164:167], v[116:119]
	v_mfma_f32_16x16x32_bf16 v[100:103], v[184:187], v[168:171], v[100:103]
	v_mfma_f32_16x16x32_bf16 v[100:103], v[188:191], v[172:175], v[100:103]
	v_mfma_f32_16x16x32_bf16 v[96:99], v[192:195], v[168:171], v[96:99]
	v_mfma_f32_16x16x32_bf16 v[96:99], v[196:199], v[172:175], v[96:99]
	v_mfma_f32_16x16x32_bf16 v[92:95], v[208:211], v[168:171], v[92:95]
	v_mfma_f32_16x16x32_bf16 v[92:95], v[212:215], v[172:175], v[92:95]
	v_mfma_f32_16x16x32_bf16 v[88:91], v[216:219], v[168:171], v[88:91]
	v_mfma_f32_16x16x32_bf16 v[88:91], v[220:223], v[172:175], v[88:91]
	v_mfma_f32_16x16x32_bf16 v[72:75], v[216:219], v[176:179], v[72:75]
	v_mfma_f32_16x16x32_bf16 v[72:75], v[220:223], v[180:183], v[72:75]
	v_mfma_f32_16x16x32_bf16 v[76:79], v[208:211], v[176:179], v[76:79]
	v_mfma_f32_16x16x32_bf16 v[76:79], v[212:215], v[180:183], v[76:79]
	v_mfma_f32_16x16x32_bf16 v[80:83], v[192:195], v[176:179], v[80:83]
	v_mfma_f32_16x16x32_bf16 v[80:83], v[196:199], v[180:183], v[80:83]
	v_mfma_f32_16x16x32_bf16 v[84:87], v[184:187], v[176:179], v[84:87]
	v_mfma_f32_16x16x32_bf16 v[84:87], v[188:191], v[180:183], v[84:87]
	s_barrier
	s_add_i32 s51, s51, s38
	v_lshl_add_u64 v[224:225], s[12:13], 0, v[138:139]
	s_mov_b32 m0, s51
	ds_read_b128 v[150:153], v155 offset:16384
	ds_read_b128 v[156:159], v155 offset:17408
	ds_read_b128 v[160:163], v155 offset:18432
	ds_read_b128 v[164:167], v155 offset:19456
	ds_read_b128 v[168:171], v155 offset:20480
	ds_read_b128 v[172:175], v155 offset:21504
	ds_read_b128 v[176:179], v155 offset:22528
	ds_read_b128 v[180:183], v155 offset:23552
	global_load_lds_dwordx4 v[224:225], off
	s_add_i32 m0, s51, 0x2000
	s_add_u32 s64, s12, 0x80000
	v_lshl_add_u64 v[226:227], s[12:13], 0, v[4:5]
	s_addc_u32 s65, s13, 0
	s_add_i32 s51, s63, s38
	global_load_lds_dwordx4 v[226:227], off
	v_lshl_add_u64 v[228:229], s[64:65], 0, v[138:139]
	s_mov_b32 m0, s51
	v_lshl_add_u64 v[230:231], s[14:15], 0, v[136:137]
	global_load_lds_dwordx4 v[228:229], off
	v_lshl_add_u64 v[228:229], s[64:65], 0, v[4:5]
	s_add_i32 m0, s51, 0x2000
	s_nop 0
	global_load_lds_dwordx4 v[228:229], off
	v_lshl_add_u64 v[228:229], s[14:15], 0, v[140:141]
	s_mov_b32 m0, s39
	s_nop 0
	global_load_lds_dwordx4 v[228:229], off
	s_mov_b32 m0, s40
	s_nop 0
	global_load_lds_dwordx4 v[230:231], off
	s_waitcnt vmcnt(8)
	s_waitcnt lgkmcnt(0)
	s_barrier
	s_waitcnt lgkmcnt(0)
	v_mfma_f32_16x16x32_bf16 v[68:71], v[184:187], v[150:153], v[68:71]
	v_mfma_f32_16x16x32_bf16 v[68:71], v[188:191], v[156:159], v[68:71]
	v_mfma_f32_16x16x32_bf16 v[64:67], v[192:195], v[150:153], v[64:67]
	v_mfma_f32_16x16x32_bf16 v[64:67], v[196:199], v[156:159], v[64:67]
	v_mfma_f32_16x16x32_bf16 v[60:63], v[208:211], v[150:153], v[60:63]
	v_mfma_f32_16x16x32_bf16 v[60:63], v[212:215], v[156:159], v[60:63]
	v_mfma_f32_16x16x32_bf16 v[56:59], v[216:219], v[150:153], v[56:59]
	v_mfma_f32_16x16x32_bf16 v[56:59], v[220:223], v[156:159], v[56:59]
	v_mfma_f32_16x16x32_bf16 v[40:43], v[216:219], v[160:163], v[40:43]
	v_mfma_f32_16x16x32_bf16 v[40:43], v[220:223], v[164:167], v[40:43]
	v_mfma_f32_16x16x32_bf16 v[44:47], v[208:211], v[160:163], v[44:47]
	v_mfma_f32_16x16x32_bf16 v[44:47], v[212:215], v[164:167], v[44:47]
	v_mfma_f32_16x16x32_bf16 v[48:51], v[192:195], v[160:163], v[48:51]
	v_mfma_f32_16x16x32_bf16 v[48:51], v[196:199], v[164:167], v[48:51]
	v_mfma_f32_16x16x32_bf16 v[52:55], v[184:187], v[160:163], v[52:55]
	v_mfma_f32_16x16x32_bf16 v[52:55], v[188:191], v[164:167], v[52:55]
	v_mfma_f32_16x16x32_bf16 v[36:39], v[184:187], v[168:171], v[36:39]
	v_mfma_f32_16x16x32_bf16 v[36:39], v[188:191], v[172:175], v[36:39]
	v_mfma_f32_16x16x32_bf16 v[32:35], v[192:195], v[168:171], v[32:35]
	v_mfma_f32_16x16x32_bf16 v[32:35], v[196:199], v[172:175], v[32:35]
	v_mfma_f32_16x16x32_bf16 v[28:31], v[208:211], v[168:171], v[28:31]
	v_mfma_f32_16x16x32_bf16 v[28:31], v[212:215], v[172:175], v[28:31]
	v_mfma_f32_16x16x32_bf16 v[24:27], v[216:219], v[168:171], v[24:27]
	v_mfma_f32_16x16x32_bf16 v[24:27], v[220:223], v[172:175], v[24:27]
	v_mfma_f32_16x16x32_bf16 v[8:11], v[216:219], v[176:179], v[8:11]
	v_mfma_f32_16x16x32_bf16 v[8:11], v[220:223], v[180:183], v[8:11]
	v_mfma_f32_16x16x32_bf16 v[12:15], v[208:211], v[176:179], v[12:15]
	v_mfma_f32_16x16x32_bf16 v[12:15], v[212:215], v[180:183], v[12:15]
	v_mfma_f32_16x16x32_bf16 v[16:19], v[192:195], v[176:179], v[16:19]
	v_mfma_f32_16x16x32_bf16 v[16:19], v[196:199], v[180:183], v[16:19]
	v_mfma_f32_16x16x32_bf16 v[20:23], v[184:187], v[176:179], v[20:23]
	v_mfma_f32_16x16x32_bf16 v[20:23], v[188:191], v[180:183], v[20:23]
	s_barrier
	s_add_i32 s51, 0, 0x18000
	s_add_i32 s63, 0, 0x1c000
	s_add_u32 s14, s14, 0x80000
	v_add_u32_e32 v2, s51, v7
	s_addc_u32 s15, s15, 0
	s_mov_b32 m0, s41
	ds_read_b128 v[150:153], v155 offset:32768
	ds_read_b128 v[156:159], v155 offset:33792
	ds_read_b128 v[160:163], v155 offset:34816
	ds_read_b128 v[164:167], v155 offset:35840
	ds_read_b128 v[168:171], v155 offset:36864
	ds_read_b128 v[172:175], v155 offset:37888
	ds_read_b128 v[176:179], v155 offset:38912
	ds_read_b128 v[180:183], v155 offset:39936
	ds_read_b128 v[184:187], v2
	ds_read_b128 v[188:191], v2 offset:1024
	ds_read_b128 v[192:195], v2 offset:2048
	ds_read_b128 v[196:199], v2 offset:3072
	v_add_u32_e32 v2, s63, v7
	v_lshl_add_u64 v[232:233], s[14:15], 0, v[140:141]
	ds_read_b128 v[208:211], v2
	ds_read_b128 v[212:215], v2 offset:1024
	ds_read_b128 v[216:219], v2 offset:2048
	ds_read_b128 v[220:223], v2 offset:3072
	global_load_lds_dwordx4 v[232:233], off
	v_lshl_add_u64 v[232:233], s[14:15], 0, v[136:137]
	s_mov_b32 m0, s47
	s_nop 0
	global_load_lds_dwordx4 v[232:233], off
	s_waitcnt vmcnt(8)
	s_waitcnt lgkmcnt(0)
	s_barrier
	s_waitcnt lgkmcnt(0)
	v_mfma_f32_16x16x32_bf16 v[132:135], v[184:187], v[150:153], v[132:135]
	v_mfma_f32_16x16x32_bf16 v[132:135], v[188:191], v[156:159], v[132:135]
	v_mfma_f32_16x16x32_bf16 v[128:131], v[192:195], v[150:153], v[128:131]
	v_mfma_f32_16x16x32_bf16 v[128:131], v[196:199], v[156:159], v[128:131]
	v_mfma_f32_16x16x32_bf16 v[124:127], v[208:211], v[150:153], v[124:127]
	v_mfma_f32_16x16x32_bf16 v[124:127], v[212:215], v[156:159], v[124:127]
	v_mfma_f32_16x16x32_bf16 v[120:123], v[216:219], v[150:153], v[120:123]
	v_mfma_f32_16x16x32_bf16 v[120:123], v[220:223], v[156:159], v[120:123]
	v_mfma_f32_16x16x32_bf16 v[104:107], v[216:219], v[160:163], v[104:107]
	v_mfma_f32_16x16x32_bf16 v[104:107], v[220:223], v[164:167], v[104:107]
	v_mfma_f32_16x16x32_bf16 v[108:111], v[208:211], v[160:163], v[108:111]
	v_mfma_f32_16x16x32_bf16 v[108:111], v[212:215], v[164:167], v[108:111]
	v_mfma_f32_16x16x32_bf16 v[112:115], v[192:195], v[160:163], v[112:115]
	v_mfma_f32_16x16x32_bf16 v[112:115], v[196:199], v[164:167], v[112:115]
	v_mfma_f32_16x16x32_bf16 v[116:119], v[184:187], v[160:163], v[116:119]
	v_mfma_f32_16x16x32_bf16 v[116:119], v[188:191], v[164:167], v[116:119]
	v_mfma_f32_16x16x32_bf16 v[100:103], v[184:187], v[168:171], v[100:103]
	v_mfma_f32_16x16x32_bf16 v[100:103], v[188:191], v[172:175], v[100:103]
	v_mfma_f32_16x16x32_bf16 v[96:99], v[192:195], v[168:171], v[96:99]
	v_mfma_f32_16x16x32_bf16 v[96:99], v[196:199], v[172:175], v[96:99]
	v_mfma_f32_16x16x32_bf16 v[92:95], v[208:211], v[168:171], v[92:95]
	v_mfma_f32_16x16x32_bf16 v[92:95], v[212:215], v[172:175], v[92:95]
	v_mfma_f32_16x16x32_bf16 v[88:91], v[216:219], v[168:171], v[88:91]
	v_mfma_f32_16x16x32_bf16 v[88:91], v[220:223], v[172:175], v[88:91]
	v_mfma_f32_16x16x32_bf16 v[72:75], v[216:219], v[176:179], v[72:75]
	v_mfma_f32_16x16x32_bf16 v[72:75], v[220:223], v[180:183], v[72:75]
	v_mfma_f32_16x16x32_bf16 v[76:79], v[208:211], v[176:179], v[76:79]
	v_mfma_f32_16x16x32_bf16 v[76:79], v[212:215], v[180:183], v[76:79]
	v_mfma_f32_16x16x32_bf16 v[80:83], v[192:195], v[176:179], v[80:83]
	v_mfma_f32_16x16x32_bf16 v[80:83], v[196:199], v[180:183], v[80:83]
	v_mfma_f32_16x16x32_bf16 v[84:87], v[184:187], v[176:179], v[84:87]
	v_mfma_f32_16x16x32_bf16 v[84:87], v[188:191], v[180:183], v[84:87]
	s_barrier
	s_add_i32 s14, s51, s38
	v_lshl_add_u64 v[224:225], v[224:225], 0, s[0:1]
	s_mov_b32 m0, s14
	ds_read_b128 v[150:153], v155 offset:49152
	ds_read_b128 v[156:159], v155 offset:50176
	ds_read_b128 v[160:163], v155 offset:51200
	ds_read_b128 v[164:167], v155 offset:52224
	ds_read_b128 v[168:171], v155 offset:53248
	ds_read_b128 v[172:175], v155 offset:54272
	ds_read_b128 v[176:179], v155 offset:55296
	ds_read_b128 v[180:183], v155 offset:56320
	global_load_lds_dwordx4 v[224:225], off
	s_add_i32 m0, s14, 0x2000
	s_add_u32 s12, s12, 0x80080
	v_lshl_add_u64 v[224:225], v[226:227], 0, s[0:1]
	s_addc_u32 s13, s13, 0
	s_add_i32 s14, s63, s38
	global_load_lds_dwordx4 v[224:225], off
	v_lshl_add_u64 v[224:225], s[12:13], 0, v[138:139]
	s_mov_b32 m0, s14
	s_nop 0
	global_load_lds_dwordx4 v[224:225], off
	v_lshl_add_u64 v[224:225], s[12:13], 0, v[4:5]
	s_add_i32 m0, s14, 0x2000
	s_nop 0
	global_load_lds_dwordx4 v[224:225], off
	v_lshl_add_u64 v[224:225], v[228:229], 0, s[0:1]
	s_mov_b32 m0, s60
	s_nop 0
	global_load_lds_dwordx4 v[224:225], off
	v_lshl_add_u64 v[224:225], v[230:231], 0, s[0:1]
	s_mov_b32 m0, s61
	s_nop 0
	global_load_lds_dwordx4 v[224:225], off
	s_waitcnt vmcnt(8)
	s_waitcnt lgkmcnt(0)
	s_barrier
	s_waitcnt lgkmcnt(0)
	v_mfma_f32_16x16x32_bf16 v[68:71], v[184:187], v[150:153], v[68:71]
	v_mfma_f32_16x16x32_bf16 v[68:71], v[188:191], v[156:159], v[68:71]
	v_mfma_f32_16x16x32_bf16 v[64:67], v[192:195], v[150:153], v[64:67]
	v_mfma_f32_16x16x32_bf16 v[64:67], v[196:199], v[156:159], v[64:67]
	v_mfma_f32_16x16x32_bf16 v[60:63], v[208:211], v[150:153], v[60:63]
	v_mfma_f32_16x16x32_bf16 v[60:63], v[212:215], v[156:159], v[60:63]
	v_mfma_f32_16x16x32_bf16 v[56:59], v[216:219], v[150:153], v[56:59]
	v_mfma_f32_16x16x32_bf16 v[56:59], v[220:223], v[156:159], v[56:59]
	v_mfma_f32_16x16x32_bf16 v[40:43], v[216:219], v[160:163], v[40:43]
	v_mfma_f32_16x16x32_bf16 v[40:43], v[220:223], v[164:167], v[40:43]
	v_mfma_f32_16x16x32_bf16 v[44:47], v[208:211], v[160:163], v[44:47]
	v_mfma_f32_16x16x32_bf16 v[44:47], v[212:215], v[164:167], v[44:47]
	v_mfma_f32_16x16x32_bf16 v[48:51], v[192:195], v[160:163], v[48:51]
	v_mfma_f32_16x16x32_bf16 v[48:51], v[196:199], v[164:167], v[48:51]
	v_mfma_f32_16x16x32_bf16 v[52:55], v[184:187], v[160:163], v[52:55]
	v_mfma_f32_16x16x32_bf16 v[52:55], v[188:191], v[164:167], v[52:55]
	v_mfma_f32_16x16x32_bf16 v[36:39], v[184:187], v[168:171], v[36:39]
	v_mfma_f32_16x16x32_bf16 v[36:39], v[188:191], v[172:175], v[36:39]
	v_mfma_f32_16x16x32_bf16 v[32:35], v[192:195], v[168:171], v[32:35]
	v_mfma_f32_16x16x32_bf16 v[32:35], v[196:199], v[172:175], v[32:35]
	v_mfma_f32_16x16x32_bf16 v[28:31], v[208:211], v[168:171], v[28:31]
	v_mfma_f32_16x16x32_bf16 v[28:31], v[212:215], v[172:175], v[28:31]
	v_mfma_f32_16x16x32_bf16 v[24:27], v[216:219], v[168:171], v[24:27]
	v_mfma_f32_16x16x32_bf16 v[24:27], v[220:223], v[172:175], v[24:27]
	v_mfma_f32_16x16x32_bf16 v[8:11], v[216:219], v[176:179], v[8:11]
	v_mfma_f32_16x16x32_bf16 v[8:11], v[220:223], v[180:183], v[8:11]
	v_mfma_f32_16x16x32_bf16 v[12:15], v[208:211], v[176:179], v[12:15]
	v_mfma_f32_16x16x32_bf16 v[12:15], v[212:215], v[180:183], v[12:15]
	v_mfma_f32_16x16x32_bf16 v[16:19], v[192:195], v[176:179], v[16:19]
	v_mfma_f32_16x16x32_bf16 v[16:19], v[196:199], v[180:183], v[16:19]
	v_mfma_f32_16x16x32_bf16 v[20:23], v[184:187], v[176:179], v[20:23]
	v_mfma_f32_16x16x32_bf16 v[20:23], v[188:191], v[180:183], v[20:23]
	s_barrier
	s_add_i32 s50, s50, 2
	s_add_u32 s44, s44, 0x100
	s_addc_u32 s45, s45, 0
	s_add_u32 s33, s33, 0x100
	s_addc_u32 s43, s43, 0
	s_cmp_gt_u32 s50, 29
	s_cbranch_scc0 .LBB0_986
	s_and_b64 vcc, exec, s[10:11]
	s_cbranch_vccz .LBB0_1031
	s_barrier
	s_cmp_gt_i32 s35, 15
	s_mov_b64 s[12:13], -1
	s_cbranch_scc1 .LBB0_1032

.LBB0_1482:
	s_add_i32 s26, s12, 2
	s_cmp_eq_u32 s57, s12
	s_cselect_b32 s13, s43, s51
	s_cselect_b32 s12, s42, s50
	s_cselect_b32 s65, s45, s15
	s_cselect_b32 s64, s44, s14
	s_add_i32 s27, 0, 0x10000
	s_movk_i32 s66, 0xff80
	v_add_u32_e32 v121, s27, v7
	s_add_i32 s63, 0, 0x14000
	v_lshl_add_u64 v[178:179], s[50:51], 0, v[108:109]
	s_mov_b32 s67, -1
	ds_read_b128 v[110:113], v119
	ds_read_b128 v[114:117], v119 offset:1024
	ds_read_b128 v[122:125], v119 offset:2048
	ds_read_b128 v[126:129], v119 offset:3072
	ds_read_b128 v[130:133], v119 offset:4096
	ds_read_b128 v[134:137], v119 offset:5120
	ds_read_b128 v[138:141], v119 offset:6144
	ds_read_b128 v[142:145], v119 offset:7168
	ds_read_b128 v[146:149], v121
	ds_read_b128 v[150:153], v121 offset:1024
	ds_read_b128 v[154:157], v121 offset:2048
	ds_read_b128 v[158:161], v121 offset:3072
	v_add_u32_e32 v121, s63, v7
	v_lshl_add_u64 v[178:179], v[178:179], 0, s[66:67]
	s_add_i32 m0, s39, 0xc000
	ds_read_b128 v[162:165], v121
	ds_read_b128 v[166:169], v121 offset:1024
	ds_read_b128 v[170:173], v121 offset:2048
	ds_read_b128 v[174:177], v121 offset:3072
	global_load_lds_dwordx4 v[178:179], off
	s_waitcnt vmcnt(7)
	s_waitcnt lgkmcnt(0)
	s_barrier
	s_waitcnt lgkmcnt(0)
	v_mfma_f32_16x16x32_bf16 v[100:103], v[146:149], v[110:113], v[100:103]
	v_mfma_f32_16x16x32_bf16 v[100:103], v[150:153], v[114:117], v[100:103]
	v_mfma_f32_16x16x32_bf16 v[96:99], v[154:157], v[110:113], v[96:99]
	v_mfma_f32_16x16x32_bf16 v[96:99], v[158:161], v[114:117], v[96:99]
	v_mfma_f32_16x16x32_bf16 v[88:91], v[162:165], v[110:113], v[88:91]
	v_mfma_f32_16x16x32_bf16 v[88:91], v[166:169], v[114:117], v[88:91]
	v_mfma_f32_16x16x32_bf16 v[84:87], v[170:173], v[110:113], v[84:87]
	v_mfma_f32_16x16x32_bf16 v[84:87], v[174:177], v[114:117], v[84:87]
	v_mfma_f32_16x16x32_bf16 v[68:71], v[170:173], v[122:125], v[68:71]
	v_mfma_f32_16x16x32_bf16 v[68:71], v[174:177], v[126:129], v[68:71]
	v_mfma_f32_16x16x32_bf16 v[76:79], v[162:165], v[122:125], v[76:79]
	v_mfma_f32_16x16x32_bf16 v[76:79], v[166:169], v[126:129], v[76:79]
	v_mfma_f32_16x16x32_bf16 v[80:83], v[154:157], v[122:125], v[80:83]
	v_mfma_f32_16x16x32_bf16 v[80:83], v[158:161], v[126:129], v[80:83]
	v_mfma_f32_16x16x32_bf16 v[92:95], v[146:149], v[122:125], v[92:95]
	v_mfma_f32_16x16x32_bf16 v[92:95], v[150:153], v[126:129], v[92:95]
	v_mfma_f32_16x16x32_bf16 v[72:75], v[146:149], v[130:133], v[72:75]
	v_mfma_f32_16x16x32_bf16 v[72:75], v[150:153], v[134:137], v[72:75]
	v_mfma_f32_16x16x32_bf16 v[64:67], v[154:157], v[130:133], v[64:67]
	v_mfma_f32_16x16x32_bf16 v[64:67], v[158:161], v[134:137], v[64:67]
	v_mfma_f32_16x16x32_bf16 v[60:63], v[162:165], v[130:133], v[60:63]
	v_mfma_f32_16x16x32_bf16 v[60:63], v[166:169], v[134:137], v[60:63]
	v_mfma_f32_16x16x32_bf16 v[52:55], v[170:173], v[130:133], v[52:55]
	v_mfma_f32_16x16x32_bf16 v[52:55], v[174:177], v[134:137], v[52:55]
	v_mfma_f32_16x16x32_bf16 v[40:43], v[170:173], v[138:141], v[40:43]
	v_mfma_f32_16x16x32_bf16 v[40:43], v[174:177], v[142:145], v[40:43]
	v_mfma_f32_16x16x32_bf16 v[44:47], v[162:165], v[138:141], v[44:47]
	v_mfma_f32_16x16x32_bf16 v[44:47], v[166:169], v[142:145], v[44:47]
	v_mfma_f32_16x16x32_bf16 v[48:51], v[154:157], v[138:141], v[48:51]
	v_mfma_f32_16x16x32_bf16 v[48:51], v[158:161], v[142:145], v[48:51]
	v_mfma_f32_16x16x32_bf16 v[56:59], v[146:149], v[138:141], v[56:59]
	v_mfma_f32_16x16x32_bf16 v[56:59], v[150:153], v[142:145], v[56:59]
	s_barrier
	s_add_i32 s27, s27, s22
	v_lshl_add_u64 v[178:179], s[64:65], 0, v[2:3]
	s_mov_b32 m0, s27
	ds_read_b128 v[110:113], v120 offset:16384
	ds_read_b128 v[114:117], v120 offset:17408
	ds_read_b128 v[122:125], v120 offset:18432
	ds_read_b128 v[126:129], v120 offset:19456
	global_load_lds_dwordx4 v[178:179], off
	s_add_i32 m0, s27, 0x2000
	v_lshl_add_u64 v[180:181], s[64:65], 0, v[4:5]
	s_add_u32 s64, s64, s90
	s_addc_u32 s65, s65, 0
	s_add_i32 s27, s63, s22
	global_load_lds_dwordx4 v[180:181], off
	v_lshl_add_u64 v[182:183], s[64:65], 0, v[2:3]
	s_mov_b32 m0, s27
	v_lshl_add_u64 v[184:185], s[64:65], 0, v[4:5]
	global_load_lds_dwordx4 v[182:183], off
	s_add_i32 m0, s27, 0x2000
	v_lshl_add_u64 v[186:187], s[12:13], 0, v[106:107]
	global_load_lds_dwordx4 v[184:185], off
	s_mov_b32 m0, s39
	v_lshl_add_u64 v[188:189], s[12:13], 0, v[104:105]
	global_load_lds_dwordx4 v[186:187], off
	s_mov_b32 m0, s40
	s_nop 0
	global_load_lds_dwordx4 v[188:189], off
	s_waitcnt vmcnt(7)
	s_waitcnt lgkmcnt(0)
	s_barrier
	s_waitcnt lgkmcnt(0)
	v_mfma_f32_16x16x32_bf16 v[36:39], v[146:149], v[110:113], v[36:39]
	v_mfma_f32_16x16x32_bf16 v[36:39], v[150:153], v[114:117], v[36:39]
	v_mfma_f32_16x16x32_bf16 v[32:35], v[154:157], v[110:113], v[32:35]
	v_mfma_f32_16x16x32_bf16 v[32:35], v[158:161], v[114:117], v[32:35]
	v_mfma_f32_16x16x32_bf16 v[28:31], v[162:165], v[110:113], v[28:31]
	v_mfma_f32_16x16x32_bf16 v[28:31], v[166:169], v[114:117], v[28:31]
	v_mfma_f32_16x16x32_bf16 v[24:27], v[170:173], v[110:113], v[24:27]
	v_mfma_f32_16x16x32_bf16 v[24:27], v[174:177], v[114:117], v[24:27]
	v_mfma_f32_16x16x32_bf16 v[20:23], v[146:149], v[122:125], v[20:23]
	v_mfma_f32_16x16x32_bf16 v[20:23], v[150:153], v[126:129], v[20:23]
	v_mfma_f32_16x16x32_bf16 v[16:19], v[154:157], v[122:125], v[16:19]
	v_mfma_f32_16x16x32_bf16 v[16:19], v[158:161], v[126:129], v[16:19]
	v_mfma_f32_16x16x32_bf16 v[12:15], v[162:165], v[122:125], v[12:15]
	v_mfma_f32_16x16x32_bf16 v[12:15], v[166:169], v[126:129], v[12:15]
	v_mfma_f32_16x16x32_bf16 v[8:11], v[170:173], v[122:125], v[8:11]
	v_mfma_f32_16x16x32_bf16 v[8:11], v[174:177], v[126:129], v[8:11]
	s_barrier
	s_add_i32 s27, 0, 0x18000
	s_add_i32 s63, 0, 0x1c000
	s_add_u32 s12, s12, s90
	v_add_u32_e32 v121, s27, v7
	s_addc_u32 s13, s13, 0
	ds_read_b128 v[110:113], v119 offset:32768
	ds_read_b128 v[114:117], v119 offset:33792
	ds_read_b128 v[122:125], v119 offset:34816
	ds_read_b128 v[126:129], v119 offset:35840
	ds_read_b128 v[130:133], v119 offset:36864
	ds_read_b128 v[134:137], v119 offset:37888
	ds_read_b128 v[138:141], v119 offset:38912
	ds_read_b128 v[142:145], v119 offset:39936
	ds_read_b128 v[146:149], v121
	ds_read_b128 v[150:153], v121 offset:1024
	ds_read_b128 v[154:157], v121 offset:2048
	ds_read_b128 v[158:161], v121 offset:3072
	v_add_u32_e32 v121, s63, v7
	v_lshl_add_u64 v[190:191], s[12:13], 0, v[106:107]
	s_mov_b32 m0, s41
	ds_read_b128 v[162:165], v121
	ds_read_b128 v[166:169], v121 offset:1024
	ds_read_b128 v[170:173], v121 offset:2048
	ds_read_b128 v[174:177], v121 offset:3072
	global_load_lds_dwordx4 v[190:191], off
	s_waitcnt vmcnt(7)
	s_waitcnt lgkmcnt(0)
	s_barrier
	s_waitcnt lgkmcnt(0)
	v_mfma_f32_16x16x32_bf16 v[100:103], v[146:149], v[110:113], v[100:103]
	v_mfma_f32_16x16x32_bf16 v[100:103], v[150:153], v[114:117], v[100:103]
	v_mfma_f32_16x16x32_bf16 v[96:99], v[154:157], v[110:113], v[96:99]
	v_mfma_f32_16x16x32_bf16 v[96:99], v[158:161], v[114:117], v[96:99]
	v_mfma_f32_16x16x32_bf16 v[88:91], v[162:165], v[110:113], v[88:91]
	v_mfma_f32_16x16x32_bf16 v[88:91], v[166:169], v[114:117], v[88:91]
	v_mfma_f32_16x16x32_bf16 v[84:87], v[170:173], v[110:113], v[84:87]
	v_mfma_f32_16x16x32_bf16 v[84:87], v[174:177], v[114:117], v[84:87]
	v_mfma_f32_16x16x32_bf16 v[68:71], v[170:173], v[122:125], v[68:71]
	v_mfma_f32_16x16x32_bf16 v[68:71], v[174:177], v[126:129], v[68:71]
	v_mfma_f32_16x16x32_bf16 v[76:79], v[162:165], v[122:125], v[76:79]
	v_mfma_f32_16x16x32_bf16 v[76:79], v[166:169], v[126:129], v[76:79]
	v_mfma_f32_16x16x32_bf16 v[80:83], v[154:157], v[122:125], v[80:83]
	v_mfma_f32_16x16x32_bf16 v[80:83], v[158:161], v[126:129], v[80:83]
	v_mfma_f32_16x16x32_bf16 v[92:95], v[146:149], v[122:125], v[92:95]
	v_mfma_f32_16x16x32_bf16 v[92:95], v[150:153], v[126:129], v[92:95]
	v_mfma_f32_16x16x32_bf16 v[72:75], v[146:149], v[130:133], v[72:75]
	v_mfma_f32_16x16x32_bf16 v[72:75], v[150:153], v[134:137], v[72:75]
	v_mfma_f32_16x16x32_bf16 v[64:67], v[154:157], v[130:133], v[64:67]
	v_mfma_f32_16x16x32_bf16 v[64:67], v[158:161], v[134:137], v[64:67]
	v_mfma_f32_16x16x32_bf16 v[60:63], v[162:165], v[130:133], v[60:63]
	v_mfma_f32_16x16x32_bf16 v[60:63], v[166:169], v[134:137], v[60:63]
	v_mfma_f32_16x16x32_bf16 v[52:55], v[170:173], v[130:133], v[52:55]
	v_mfma_f32_16x16x32_bf16 v[52:55], v[174:177], v[134:137], v[52:55]
	v_mfma_f32_16x16x32_bf16 v[40:43], v[170:173], v[138:141], v[40:43]
	v_mfma_f32_16x16x32_bf16 v[40:43], v[174:177], v[142:145], v[40:43]
	v_mfma_f32_16x16x32_bf16 v[44:47], v[162:165], v[138:141], v[44:47]
	v_mfma_f32_16x16x32_bf16 v[44:47], v[166:169], v[142:145], v[44:47]
	v_mfma_f32_16x16x32_bf16 v[48:51], v[154:157], v[138:141], v[48:51]
	v_mfma_f32_16x16x32_bf16 v[48:51], v[158:161], v[142:145], v[48:51]
	v_mfma_f32_16x16x32_bf16 v[56:59], v[146:149], v[138:141], v[56:59]
	v_mfma_f32_16x16x32_bf16 v[56:59], v[150:153], v[142:145], v[56:59]
	s_barrier
	s_add_i32 s12, s27, s22
	v_lshl_add_u64 v[130:131], v[178:179], 0, s[0:1]
	s_mov_b32 m0, s12
	ds_read_b128 v[110:113], v120 offset:49152
	ds_read_b128 v[114:117], v120 offset:50176
	ds_read_b128 v[122:125], v120 offset:51200
	ds_read_b128 v[126:129], v120 offset:52224
	global_load_lds_dwordx4 v[130:131], off
	v_lshl_add_u64 v[130:131], v[180:181], 0, s[0:1]
	s_add_i32 m0, s12, 0x2000
	s_add_i32 s12, s63, s22
	global_load_lds_dwordx4 v[130:131], off
	v_lshl_add_u64 v[130:131], v[182:183], 0, s[0:1]
	s_mov_b32 m0, s12
	s_nop 0
	global_load_lds_dwordx4 v[130:131], off
	v_lshl_add_u64 v[130:131], v[184:185], 0, s[0:1]
	s_add_i32 m0, s12, 0x2000
	s_nop 0
	global_load_lds_dwordx4 v[130:131], off
	v_lshl_add_u64 v[130:131], v[186:187], 0, s[0:1]
	s_mov_b32 m0, s53
	s_nop 0
	global_load_lds_dwordx4 v[130:131], off
	v_lshl_add_u64 v[130:131], v[188:189], 0, s[0:1]
	s_mov_b32 m0, s54
	s_nop 0
	global_load_lds_dwordx4 v[130:131], off
	s_waitcnt vmcnt(7)
	s_waitcnt lgkmcnt(0)
	s_barrier
	s_waitcnt lgkmcnt(0)
	v_mfma_f32_16x16x32_bf16 v[36:39], v[146:149], v[110:113], v[36:39]
	v_mfma_f32_16x16x32_bf16 v[36:39], v[150:153], v[114:117], v[36:39]
	v_mfma_f32_16x16x32_bf16 v[32:35], v[154:157], v[110:113], v[32:35]
	v_mfma_f32_16x16x32_bf16 v[32:35], v[158:161], v[114:117], v[32:35]
	v_mfma_f32_16x16x32_bf16 v[28:31], v[162:165], v[110:113], v[28:31]
	v_mfma_f32_16x16x32_bf16 v[28:31], v[166:169], v[114:117], v[28:31]
	v_mfma_f32_16x16x32_bf16 v[24:27], v[170:173], v[110:113], v[24:27]
	v_mfma_f32_16x16x32_bf16 v[24:27], v[174:177], v[114:117], v[24:27]
	v_mfma_f32_16x16x32_bf16 v[20:23], v[146:149], v[122:125], v[20:23]
	v_mfma_f32_16x16x32_bf16 v[20:23], v[150:153], v[126:129], v[20:23]
	v_mfma_f32_16x16x32_bf16 v[16:19], v[154:157], v[122:125], v[16:19]
	v_mfma_f32_16x16x32_bf16 v[16:19], v[158:161], v[126:129], v[16:19]
	v_mfma_f32_16x16x32_bf16 v[12:15], v[162:165], v[122:125], v[12:15]
	v_mfma_f32_16x16x32_bf16 v[12:15], v[166:169], v[126:129], v[12:15]
	v_mfma_f32_16x16x32_bf16 v[8:11], v[170:173], v[122:125], v[8:11]
	v_mfma_f32_16x16x32_bf16 v[8:11], v[174:177], v[126:129], v[8:11]
	s_barrier
	s_add_u32 s50, s50, 0x100
	s_addc_u32 s51, s51, 0
	s_add_u32 s14, s14, 0x100
	s_addc_u32 s15, s15, 0
	s_cmp_ge_u32 s26, s55
	s_mov_b32 s12, s26
	s_cbranch_scc0 .LBB0_1482
	s_and_b64 vcc, exec, s[36:37]
	s_cbranch_vccz .LBB0_1485
	s_barrier
